# K-loop: delete the mid-segment s_setprio 0/1 flip pairs (one priority window per 32-MFMA segment)
# baseline (speedup 1.0000x reference)
; #define PG8_STAGE(bufoff, gbase, voff) do { _Pragma("unroll") for (int _i = 0; _i < 2; ++_i) \
;         __builtin_amdgcn_global_load_lds((const unsigned*)((const char*)(gbase) + (voff)[_i]), (PG8_LAS unsigned*)(lds + (bufoff) + ldsw + _i * 8192), 16, 0, 0); } while (0)
; #define PG8_LDA(dst, b, h) do { _Pragma("unroll") for (int m = 0; m < 4; ++m) _Pragma("unroll") for (int k = 0; k < 2; ++k) dst[m][k] = *(const PG8_LAS bf16x8*)(lds + PG8_SA(b, h) + aoff + m * 2048 + k * 1024); } while (0)
; #define PG8_LDB(dst, b, h) do { _Pragma("unroll") for (int n = 0; n < 2; ++n) _Pragma("unroll") for (int k = 0; k < 2; ++k) dst[n][k] = *(const PG8_LAS bf16x8*)(lds + PG8_SB(b, h) + boff + n * 2048 + k * 1024); } while (0)
; #define PG8_MMA(ai, bj, At, Bt) do { __builtin_amdgcn_s_setprio(1); _Pragma("unroll") for (int m = 0; m < 4; ++m) _Pragma("unroll") for (int n = 0; n < 2; ++n) _Pragma("unroll") for (int k = 0; k < 2; ++k) \
;         acc[ai][bj][m][n] = __builtin_amdgcn_mfma_f32_16x16x32_bf16(Bt[n][k], At[m][k], acc[ai][bj][m][n], 0, 0, 0); __builtin_amdgcn_s_setprio(0); } while (0)
; #define PG8_WAIT_V(n) asm volatile("s_waitcnt vmcnt(" #n ")" ::: "memory")
; #define PG8_WAIT_L(n) asm volatile("s_waitcnt lgkmcnt(" #n ")" ::: "memory")
; template <class Epi, class Sched, bool ALIGN_EPI = false, bool SP2 = false>
; __device__ __forceinline__ void gemm_phase(PG8_LAS unsigned char* lds, const Gemm g, const Sched& S, const Epi& E) {
;     ...
;             const bool last = (t == nt - 2);
;             const char* a1 = cA + (size_t)(t + 1) * kstep;
;             const char* a2 = last ? nA : cA + (size_t)(t + 2) * kstep; const char* b2 = last ? nB : cB + (size_t)(t + 2) * kstep;
;             const char* a3 = a2 + kstep; const char* b3 = b2 + kstep;
;             if (last && has_next) S.a_ready(nxt);
;             if constexpr (SP2) {
;             PG8_LDB(B0, 0, 0); PG8_LDB(B1, 0, 1); PG8_SCHED; PG8_LDA(At, 0, 0); PG8_STAGE(PG8_SA(1, 1), a1 + hstep, voffA);
;             PG8_WAIT_V(8); PG8_WAIT_L(0); PG8_BAR; PG8_MMA(0, 0, At, B0); PG8_MMA(0, 1, At, B1); PG8_BAR; PG8_SCHED;
;             if (full) PG8_LDA(At, 0, 1); PG8_STAGE(PG8_SB(0, 0), b2, voffB); PG8_STAGE(PG8_SB(0, 1), b2 + hstep, voffB); PG8_STAGE(PG8_SA(0, 0), a2, voffA);
;             PG8_WAIT_V(8); PG8_WAIT_L(0); PG8_BAR; if (full) { PG8_MMA(1, 0, At, B0); PG8_MMA(1, 1, At, B1); } PG8_BAR; PG8_SCHED;
.LBB0_292:
	v_add_u32_e32 v0, 0x10000, v223
	ds_read_b128 v[148:151], v0
	ds_read_b128 v[152:155], v0 offset:1024
	ds_read_b128 v[156:159], v0 offset:2048
	ds_read_b128 v[160:163], v0 offset:3072
	v_add_u32_e32 v0, 0x14000, v223
	ds_read_b128 v[132:135], v0
	ds_read_b128 v[136:139], v0 offset:1024
	ds_read_b128 v[140:143], v0 offset:2048
	ds_read_b128 v[144:147], v0 offset:3072
	v_lshl_add_u64 v[2:3], s[36:37], 0, v[204:205]
	s_add_i32 m0, s31, 0xc000
	ds_read_b128 v[176:179], v224
	ds_read_b128 v[192:195], v224 offset:1024
	ds_read_b128 v[172:175], v224 offset:2048
	ds_read_b128 v[188:191], v224 offset:3072
	ds_read_b128 v[168:171], v224 offset:4096
	ds_read_b128 v[184:187], v224 offset:5120
	ds_read_b128 v[164:167], v224 offset:6144
	ds_read_b128 v[180:183], v224 offset:7168
	global_load_lds_dwordx4 v[2:3], off
	v_lshl_add_u64 v[2:3], s[36:37], 0, v[206:207]
	s_add_i32 m0, s31, 0xe000
	s_nop 0
	global_load_lds_dwordx4 v[2:3], off
	s_waitcnt vmcnt(8)
	s_waitcnt lgkmcnt(0)
	s_setprio 1
	s_barrier
	s_waitcnt lgkmcnt(0)
	v_mfma_f32_16x16x32_bf16 v[128:131], v[148:151], v[176:179], v[128:131]
	v_mfma_f32_16x16x32_bf16 v[124:127], v[156:159], v[176:179], v[124:127]
	v_mfma_f32_16x16x32_bf16 v[112:115], v[148:151], v[172:175], v[112:115]
	v_mfma_f32_16x16x32_bf16 v[108:111], v[156:159], v[172:175], v[108:111]
	v_mfma_f32_16x16x32_bf16 v[96:99], v[148:151], v[168:171], v[96:99]
	v_mfma_f32_16x16x32_bf16 v[92:95], v[156:159], v[168:171], v[92:95]
	v_mfma_f32_16x16x32_bf16 v[80:83], v[148:151], v[164:167], v[80:83]
	v_mfma_f32_16x16x32_bf16 v[76:79], v[156:159], v[164:167], v[76:79]
	v_mfma_f32_16x16x32_bf16 v[128:131], v[152:155], v[192:195], v[128:131]
	v_mfma_f32_16x16x32_bf16 v[124:127], v[160:163], v[192:195], v[124:127]
	v_mfma_f32_16x16x32_bf16 v[112:115], v[152:155], v[188:191], v[112:115]
	v_mfma_f32_16x16x32_bf16 v[108:111], v[160:163], v[188:191], v[108:111]
	v_mfma_f32_16x16x32_bf16 v[96:99], v[152:155], v[184:187], v[96:99]
	v_mfma_f32_16x16x32_bf16 v[92:95], v[160:163], v[184:187], v[92:95]
	v_mfma_f32_16x16x32_bf16 v[80:83], v[152:155], v[180:183], v[80:83]
	v_mfma_f32_16x16x32_bf16 v[76:79], v[160:163], v[180:183], v[76:79]
	v_mfma_f32_16x16x32_bf16 v[120:123], v[132:135], v[176:179], v[120:123]
	v_mfma_f32_16x16x32_bf16 v[116:119], v[140:143], v[176:179], v[116:119]
	v_mfma_f32_16x16x32_bf16 v[104:107], v[132:135], v[172:175], v[104:107]
	v_mfma_f32_16x16x32_bf16 v[100:103], v[140:143], v[172:175], v[100:103]
	v_mfma_f32_16x16x32_bf16 v[88:91], v[132:135], v[168:171], v[88:91]
	v_mfma_f32_16x16x32_bf16 v[84:87], v[140:143], v[168:171], v[84:87]
	v_mfma_f32_16x16x32_bf16 v[72:75], v[132:135], v[164:167], v[72:75]
	v_mfma_f32_16x16x32_bf16 v[68:71], v[140:143], v[164:167], v[68:71]
	v_mfma_f32_16x16x32_bf16 v[120:123], v[136:139], v[192:195], v[120:123]
	v_mfma_f32_16x16x32_bf16 v[116:119], v[144:147], v[192:195], v[116:119]
	v_mfma_f32_16x16x32_bf16 v[104:107], v[136:139], v[188:191], v[104:107]
	v_mfma_f32_16x16x32_bf16 v[100:103], v[144:147], v[188:191], v[100:103]
	v_mfma_f32_16x16x32_bf16 v[88:91], v[136:139], v[184:187], v[88:91]
	v_mfma_f32_16x16x32_bf16 v[84:87], v[144:147], v[184:187], v[84:87]
	v_mfma_f32_16x16x32_bf16 v[72:75], v[136:139], v[180:183], v[72:75]
	v_mfma_f32_16x16x32_bf16 v[68:71], v[144:147], v[180:183], v[68:71]
	s_barrier
	s_setprio 0
	v_cndmask_b32_e64 v0, 0, 1, s[34:35]
	v_cmp_ne_u32_e64 s[4:5], 1, v0
	s_andn2_b64 vcc, exec, s[34:35]
	s_cbranch_vccnz .LBB0_294
	ds_read_b128 v[176:179], v224 offset:16384
	ds_read_b128 v[192:195], v224 offset:17408
	ds_read_b128 v[172:175], v224 offset:18432
	ds_read_b128 v[188:191], v224 offset:19456
	ds_read_b128 v[168:171], v224 offset:20480
	ds_read_b128 v[184:187], v224 offset:21504
	ds_read_b128 v[164:167], v224 offset:22528
	ds_read_b128 v[180:183], v224 offset:23552
.LBB0_294:
	s_add_u32 s38, s36, 0xfffc0080
	s_addc_u32 s39, s37, -1
	s_cmp_eq_u32 s89, 12
	s_cselect_b32 s43, s23, s39
	s_cselect_b32 s42, s81, s38
	s_cselect_b32 s39, s21, s88
	s_cselect_b32 s38, s82, s83
	s_mov_b32 m0, s54
	v_lshl_add_u64 v[2:3], s[38:39], 0, v[198:199]
	s_add_u32 s90, s38, 0x40000
	global_load_lds_dwordx4 v[2:3], off
	v_lshl_add_u64 v[208:209], s[38:39], 0, v[202:203]
	s_mov_b32 m0, s55
	s_addc_u32 s91, s39, 0
	global_load_lds_dwordx4 v[208:209], off
	v_lshl_add_u64 v[210:211], s[90:91], 0, v[198:199]
	s_mov_b32 m0, s56
	v_lshl_add_u64 v[220:221], s[42:43], 0, v[200:201]
	global_load_lds_dwordx4 v[210:211], off
	v_lshl_add_u64 v[210:211], s[90:91], 0, v[202:203]
	s_mov_b32 m0, s57
	s_and_b64 vcc, exec, s[4:5]
	global_load_lds_dwordx4 v[210:211], off
	v_lshl_add_u64 v[210:211], s[42:43], 0, v[196:197]
	s_mov_b32 m0, s31
	s_nop 0
	global_load_lds_dwordx4 v[210:211], off
	s_mov_b32 m0, s58
	s_nop 0
	global_load_lds_dwordx4 v[220:221], off
	s_waitcnt vmcnt(8)
	s_waitcnt lgkmcnt(0)
	s_setprio 1
	s_barrier
	s_cbranch_vccnz .LBB0_296
; #define PG8_STAGE(bufoff, gbase, voff) do { _Pragma("unroll") for (int _i = 0; _i < 2; ++_i) \
;         __builtin_amdgcn_global_load_lds((const unsigned*)((const char*)(gbase) + (voff)[_i]), (PG8_LAS unsigned*)(lds + (bufoff) + ldsw + _i * 8192), 16, 0, 0); } while (0)
; #define PG8_LDA(dst, b, h) do { _Pragma("unroll") for (int m = 0; m < 4; ++m) _Pragma("unroll") for (int k = 0; k < 2; ++k) dst[m][k] = *(const PG8_LAS bf16x8*)(lds + PG8_SA(b, h) + aoff + m * 2048 + k * 1024); } while (0)
; #define PG8_LDB(dst, b, h) do { _Pragma("unroll") for (int n = 0; n < 2; ++n) _Pragma("unroll") for (int k = 0; k < 2; ++k) dst[n][k] = *(const PG8_LAS bf16x8*)(lds + PG8_SB(b, h) + boff + n * 2048 + k * 1024); } while (0)
; #define PG8_MMA(ai, bj, At, Bt) do { __builtin_amdgcn_s_setprio(1); _Pragma("unroll") for (int m = 0; m < 4; ++m) _Pragma("unroll") for (int n = 0; n < 2; ++n) _Pragma("unroll") for (int k = 0; k < 2; ++k) \
;         acc[ai][bj][m][n] = __builtin_amdgcn_mfma_f32_16x16x32_bf16(Bt[n][k], At[m][k], acc[ai][bj][m][n], 0, 0, 0); __builtin_amdgcn_s_setprio(0); } while (0)
; #define PG8_WAIT_V(n) asm volatile("s_waitcnt vmcnt(" #n ")" ::: "memory")
; #define PG8_WAIT_L(n) asm volatile("s_waitcnt lgkmcnt(" #n ")" ::: "memory")
; #define PG8_BAR __builtin_amdgcn_s_barrier()
; #define PG8_SCHED __builtin_amdgcn_sched_barrier(0)
; template <class Epi, class Sched, bool ALIGN_EPI = false, bool SP2 = false>
; __device__ __forceinline__ void gemm_phase(PG8_LAS unsigned char* lds, const Gemm g, const Sched& S, const Epi& E) {
;     ...
;             PG8_WAIT_V(8); PG8_WAIT_L(0); PG8_BAR; if (full) { PG8_MMA(1, 0, At, B0); PG8_MMA(1, 1, At, B1); } PG8_BAR; PG8_SCHED;
;             PG8_LDB(B0, 1, 0); PG8_LDB(B1, 1, 1); PG8_SCHED; PG8_LDA(At, 1, 0); PG8_STAGE(PG8_SA(0, 1), a2 + hstep, voffA);
;             PG8_WAIT_V(8); PG8_WAIT_L(0); PG8_BAR; PG8_MMA(0, 0, At, B0); PG8_MMA(0, 1, At, B1); PG8_BAR; PG8_SCHED;
;             if (full) PG8_LDA(At, 1, 1); PG8_STAGE(PG8_SB(1, 0), b3, voffB); PG8_STAGE(PG8_SB(1, 1), b3 + hstep, voffB); PG8_STAGE(PG8_SA(1, 0), a3, voffA);
	s_setprio 1
	s_waitcnt lgkmcnt(0)
	v_mfma_f32_16x16x32_bf16 v[64:67], v[148:151], v[176:179], v[64:67]
	v_mfma_f32_16x16x32_bf16 v[56:59], v[156:159], v[176:179], v[56:59]
	v_mfma_f32_16x16x32_bf16 v[48:51], v[148:151], v[172:175], v[48:51]
	v_mfma_f32_16x16x32_bf16 v[40:43], v[156:159], v[172:175], v[40:43]
	v_mfma_f32_16x16x32_bf16 v[32:35], v[148:151], v[168:171], v[32:35]
	v_mfma_f32_16x16x32_bf16 v[24:27], v[156:159], v[168:171], v[24:27]
	v_mfma_f32_16x16x32_bf16 v[16:19], v[148:151], v[164:167], v[16:19]
	v_mfma_f32_16x16x32_bf16 v[8:11], v[156:159], v[164:167], v[8:11]
	v_mfma_f32_16x16x32_bf16 v[64:67], v[152:155], v[192:195], v[64:67]
	v_mfma_f32_16x16x32_bf16 v[56:59], v[160:163], v[192:195], v[56:59]
	v_mfma_f32_16x16x32_bf16 v[48:51], v[152:155], v[188:191], v[48:51]
	v_mfma_f32_16x16x32_bf16 v[40:43], v[160:163], v[188:191], v[40:43]
	v_mfma_f32_16x16x32_bf16 v[32:35], v[152:155], v[184:187], v[32:35]
	v_mfma_f32_16x16x32_bf16 v[24:27], v[160:163], v[184:187], v[24:27]
	v_mfma_f32_16x16x32_bf16 v[16:19], v[152:155], v[180:183], v[16:19]
	v_mfma_f32_16x16x32_bf16 v[8:11], v[160:163], v[180:183], v[8:11]
	v_mfma_f32_16x16x32_bf16 v[60:63], v[132:135], v[176:179], v[60:63]
	v_mfma_f32_16x16x32_bf16 v[52:55], v[140:143], v[176:179], v[52:55]
	v_mfma_f32_16x16x32_bf16 v[44:47], v[132:135], v[172:175], v[44:47]
	v_mfma_f32_16x16x32_bf16 v[36:39], v[140:143], v[172:175], v[36:39]
	v_mfma_f32_16x16x32_bf16 v[28:31], v[132:135], v[168:171], v[28:31]
	v_mfma_f32_16x16x32_bf16 v[20:23], v[140:143], v[168:171], v[20:23]
	v_mfma_f32_16x16x32_bf16 v[12:15], v[132:135], v[164:167], v[12:15]
	v_mfma_f32_16x16x32_bf16 v[4:7], v[140:143], v[164:167], v[4:7]
	v_mfma_f32_16x16x32_bf16 v[60:63], v[136:139], v[192:195], v[60:63]
	v_mfma_f32_16x16x32_bf16 v[52:55], v[144:147], v[192:195], v[52:55]
	v_mfma_f32_16x16x32_bf16 v[44:47], v[136:139], v[188:191], v[44:47]
	v_mfma_f32_16x16x32_bf16 v[36:39], v[144:147], v[188:191], v[36:39]
	v_mfma_f32_16x16x32_bf16 v[28:31], v[136:139], v[184:187], v[28:31]
	v_mfma_f32_16x16x32_bf16 v[20:23], v[144:147], v[184:187], v[20:23]
	v_mfma_f32_16x16x32_bf16 v[12:15], v[136:139], v[180:183], v[12:15]
	v_mfma_f32_16x16x32_bf16 v[4:7], v[144:147], v[180:183], v[4:7]
.LBB0_296:
	s_barrier
	s_setprio 0
	v_add_u32_e32 v0, 0x18000, v223
	ds_read_b128 v[148:151], v0
	ds_read_b128 v[152:155], v0 offset:1024
	ds_read_b128 v[156:159], v0 offset:2048
	ds_read_b128 v[160:163], v0 offset:3072
	v_add_u32_e32 v0, 0x1c000, v223
	ds_read_b128 v[132:135], v0
	ds_read_b128 v[136:139], v0 offset:1024
	ds_read_b128 v[140:143], v0 offset:2048
	ds_read_b128 v[144:147], v0 offset:3072
	s_add_u32 s42, s42, 0x40000
	s_addc_u32 s43, s43, 0
	s_mov_b32 m0, s59
	v_lshl_add_u64 v[212:213], s[42:43], 0, v[196:197]
	ds_read_b128 v[176:179], v224 offset:32768
	ds_read_b128 v[192:195], v224 offset:33792
	ds_read_b128 v[172:175], v224 offset:34816
	ds_read_b128 v[188:191], v224 offset:35840
	ds_read_b128 v[168:171], v224 offset:36864
	ds_read_b128 v[184:187], v224 offset:37888
	ds_read_b128 v[164:167], v224 offset:38912
	ds_read_b128 v[180:183], v224 offset:39936
	global_load_lds_dwordx4 v[212:213], off
	v_lshl_add_u64 v[212:213], s[42:43], 0, v[200:201]
	s_mov_b32 m0, s60
	s_nop 0
	global_load_lds_dwordx4 v[212:213], off
	s_waitcnt vmcnt(8)
	s_waitcnt lgkmcnt(0)
	s_setprio 1
	s_barrier
	s_waitcnt lgkmcnt(0)
	v_mfma_f32_16x16x32_bf16 v[128:131], v[148:151], v[176:179], v[128:131]
	v_mfma_f32_16x16x32_bf16 v[124:127], v[156:159], v[176:179], v[124:127]
	v_mfma_f32_16x16x32_bf16 v[112:115], v[148:151], v[172:175], v[112:115]
	v_mfma_f32_16x16x32_bf16 v[108:111], v[156:159], v[172:175], v[108:111]
	v_mfma_f32_16x16x32_bf16 v[96:99], v[148:151], v[168:171], v[96:99]
	v_mfma_f32_16x16x32_bf16 v[92:95], v[156:159], v[168:171], v[92:95]
	v_mfma_f32_16x16x32_bf16 v[80:83], v[148:151], v[164:167], v[80:83]
	v_mfma_f32_16x16x32_bf16 v[76:79], v[156:159], v[164:167], v[76:79]
	v_mfma_f32_16x16x32_bf16 v[128:131], v[152:155], v[192:195], v[128:131]
	v_mfma_f32_16x16x32_bf16 v[124:127], v[160:163], v[192:195], v[124:127]
	v_mfma_f32_16x16x32_bf16 v[112:115], v[152:155], v[188:191], v[112:115]
	v_mfma_f32_16x16x32_bf16 v[108:111], v[160:163], v[188:191], v[108:111]
	v_mfma_f32_16x16x32_bf16 v[96:99], v[152:155], v[184:187], v[96:99]
	v_mfma_f32_16x16x32_bf16 v[92:95], v[160:163], v[184:187], v[92:95]
	v_mfma_f32_16x16x32_bf16 v[80:83], v[152:155], v[180:183], v[80:83]
	v_mfma_f32_16x16x32_bf16 v[76:79], v[160:163], v[180:183], v[76:79]
	v_mfma_f32_16x16x32_bf16 v[120:123], v[132:135], v[176:179], v[120:123]
	v_mfma_f32_16x16x32_bf16 v[116:119], v[140:143], v[176:179], v[116:119]
	v_mfma_f32_16x16x32_bf16 v[104:107], v[132:135], v[172:175], v[104:107]
	v_mfma_f32_16x16x32_bf16 v[100:103], v[140:143], v[172:175], v[100:103]
	v_mfma_f32_16x16x32_bf16 v[88:91], v[132:135], v[168:171], v[88:91]
	v_mfma_f32_16x16x32_bf16 v[84:87], v[140:143], v[168:171], v[84:87]
	v_mfma_f32_16x16x32_bf16 v[72:75], v[132:135], v[164:167], v[72:75]
	v_mfma_f32_16x16x32_bf16 v[68:71], v[140:143], v[164:167], v[68:71]
	v_mfma_f32_16x16x32_bf16 v[120:123], v[136:139], v[192:195], v[120:123]
	v_mfma_f32_16x16x32_bf16 v[116:119], v[144:147], v[192:195], v[116:119]
	v_mfma_f32_16x16x32_bf16 v[104:107], v[136:139], v[188:191], v[104:107]
	v_mfma_f32_16x16x32_bf16 v[100:103], v[144:147], v[188:191], v[100:103]
	v_mfma_f32_16x16x32_bf16 v[88:91], v[136:139], v[184:187], v[88:91]
	v_mfma_f32_16x16x32_bf16 v[84:87], v[144:147], v[184:187], v[84:87]
	v_mfma_f32_16x16x32_bf16 v[72:75], v[136:139], v[180:183], v[72:75]
	v_mfma_f32_16x16x32_bf16 v[68:71], v[144:147], v[180:183], v[68:71]
	s_barrier
	s_setprio 0
	s_and_b64 vcc, exec, s[4:5]
	s_cbranch_vccnz .LBB0_298
	ds_read_b128 v[176:179], v224 offset:49152
	ds_read_b128 v[192:195], v224 offset:50176
	ds_read_b128 v[172:175], v224 offset:51200
	ds_read_b128 v[188:191], v224 offset:52224
	ds_read_b128 v[168:171], v224 offset:53248
	ds_read_b128 v[184:187], v224 offset:54272
	ds_read_b128 v[164:167], v224 offset:55296
	ds_read_b128 v[180:183], v224 offset:56320
; #define PG8_STAGE(bufoff, gbase, voff) do { _Pragma("unroll") for (int _i = 0; _i < 2; ++_i) \
;         __builtin_amdgcn_global_load_lds((const unsigned*)((const char*)(gbase) + (voff)[_i]), (PG8_LAS unsigned*)(lds + (bufoff) + ldsw + _i * 8192), 16, 0, 0); } while (0)
; #define PG8_LDA(dst, b, h) do { _Pragma("unroll") for (int m = 0; m < 4; ++m) _Pragma("unroll") for (int k = 0; k < 2; ++k) dst[m][k] = *(const PG8_LAS bf16x8*)(lds + PG8_SA(b, h) + aoff + m * 2048 + k * 1024); } while (0)
; #define PG8_MMA(ai, bj, At, Bt) do { __builtin_amdgcn_s_setprio(1); _Pragma("unroll") for (int m = 0; m < 4; ++m) _Pragma("unroll") for (int n = 0; n < 2; ++n) _Pragma("unroll") for (int k = 0; k < 2; ++k) \
;         acc[ai][bj][m][n] = __builtin_amdgcn_mfma_f32_16x16x32_bf16(Bt[n][k], At[m][k], acc[ai][bj][m][n], 0, 0, 0); __builtin_amdgcn_s_setprio(0); } while (0)
; #define PG8_WAIT_V(n) asm volatile("s_waitcnt vmcnt(" #n ")" ::: "memory")
; #define PG8_WAIT_L(n) asm volatile("s_waitcnt lgkmcnt(" #n ")" ::: "memory")
; #define PG8_BAR __builtin_amdgcn_s_barrier()
; #define PG8_SCHED __builtin_amdgcn_sched_barrier(0)
; template <class Epi, class Sched, bool ALIGN_EPI = false, bool SP2 = false>
; __device__ __forceinline__ void gemm_phase(PG8_LAS unsigned char* lds, const Gemm g, const Sched& S, const Epi& E) {
;     ...
;             if (full) PG8_LDA(At, 1, 1); PG8_STAGE(PG8_SB(1, 0), b3, voffB); PG8_STAGE(PG8_SB(1, 1), b3 + hstep, voffB); PG8_STAGE(PG8_SA(1, 0), a3, voffA);
;             PG8_WAIT_V(8); PG8_WAIT_L(0); PG8_BAR; if (full) { PG8_MMA(1, 0, At, B0); PG8_MMA(1, 1, At, B1); } PG8_BAR; PG8_SCHED;
.LBB0_298:
	s_mov_b32 m0, s61
	v_lshl_add_u64 v[2:3], v[2:3], 0, s[52:53]
	s_add_u32 s38, s38, 0x40080
	global_load_lds_dwordx4 v[2:3], off
	v_lshl_add_u64 v[2:3], v[208:209], 0, s[52:53]
	s_mov_b32 m0, s62
	s_addc_u32 s39, s39, 0
	global_load_lds_dwordx4 v[2:3], off
	v_lshl_add_u64 v[2:3], s[38:39], 0, v[198:199]
	s_mov_b32 m0, s65
	s_and_b64 vcc, exec, s[4:5]
	global_load_lds_dwordx4 v[2:3], off
	v_lshl_add_u64 v[2:3], s[38:39], 0, v[202:203]
	s_mov_b32 m0, s68
	s_nop 0
	global_load_lds_dwordx4 v[2:3], off
	v_lshl_add_u64 v[2:3], v[210:211], 0, s[52:53]
	s_mov_b32 m0, s63
	s_nop 0
	global_load_lds_dwordx4 v[2:3], off
	v_lshl_add_u64 v[2:3], v[220:221], 0, s[52:53]
	s_mov_b32 m0, s64
	s_nop 0
	global_load_lds_dwordx4 v[2:3], off
	s_waitcnt vmcnt(8)
	s_waitcnt lgkmcnt(0)
	s_setprio 1
	s_barrier
	s_cbranch_vccnz .LBB0_291
	s_setprio 1
	s_waitcnt lgkmcnt(0)
	v_mfma_f32_16x16x32_bf16 v[64:67], v[148:151], v[176:179], v[64:67]
	v_mfma_f32_16x16x32_bf16 v[56:59], v[156:159], v[176:179], v[56:59]
	v_mfma_f32_16x16x32_bf16 v[48:51], v[148:151], v[172:175], v[48:51]
	v_mfma_f32_16x16x32_bf16 v[40:43], v[156:159], v[172:175], v[40:43]
	v_mfma_f32_16x16x32_bf16 v[32:35], v[148:151], v[168:171], v[32:35]
	v_mfma_f32_16x16x32_bf16 v[24:27], v[156:159], v[168:171], v[24:27]
	v_mfma_f32_16x16x32_bf16 v[16:19], v[148:151], v[164:167], v[16:19]
	v_mfma_f32_16x16x32_bf16 v[8:11], v[156:159], v[164:167], v[8:11]
	v_mfma_f32_16x16x32_bf16 v[64:67], v[152:155], v[192:195], v[64:67]
	v_mfma_f32_16x16x32_bf16 v[56:59], v[160:163], v[192:195], v[56:59]
	v_mfma_f32_16x16x32_bf16 v[48:51], v[152:155], v[188:191], v[48:51]
	v_mfma_f32_16x16x32_bf16 v[40:43], v[160:163], v[188:191], v[40:43]
	v_mfma_f32_16x16x32_bf16 v[32:35], v[152:155], v[184:187], v[32:35]
	v_mfma_f32_16x16x32_bf16 v[24:27], v[160:163], v[184:187], v[24:27]
	v_mfma_f32_16x16x32_bf16 v[16:19], v[152:155], v[180:183], v[16:19]
	v_mfma_f32_16x16x32_bf16 v[8:11], v[160:163], v[180:183], v[8:11]
	v_mfma_f32_16x16x32_bf16 v[60:63], v[132:135], v[176:179], v[60:63]
	v_mfma_f32_16x16x32_bf16 v[52:55], v[140:143], v[176:179], v[52:55]
	v_mfma_f32_16x16x32_bf16 v[44:47], v[132:135], v[172:175], v[44:47]
	v_mfma_f32_16x16x32_bf16 v[36:39], v[140:143], v[172:175], v[36:39]
	v_mfma_f32_16x16x32_bf16 v[28:31], v[132:135], v[168:171], v[28:31]
	v_mfma_f32_16x16x32_bf16 v[20:23], v[140:143], v[168:171], v[20:23]
	v_mfma_f32_16x16x32_bf16 v[12:15], v[132:135], v[164:167], v[12:15]
	v_mfma_f32_16x16x32_bf16 v[2:5], v[140:143], v[164:167], v[4:7]
	v_mfma_f32_16x16x32_bf16 v[60:63], v[136:139], v[192:195], v[60:63]
	v_mfma_f32_16x16x32_bf16 v[52:55], v[144:147], v[192:195], v[52:55]
	v_mfma_f32_16x16x32_bf16 v[44:47], v[136:139], v[188:191], v[44:47]
	v_mfma_f32_16x16x32_bf16 v[36:39], v[144:147], v[188:191], v[36:39]
	v_mfma_f32_16x16x32_bf16 v[28:31], v[136:139], v[184:187], v[28:31]
	v_mfma_f32_16x16x32_bf16 v[20:23], v[144:147], v[184:187], v[20:23]
	v_mfma_f32_16x16x32_bf16 v[12:15], v[136:139], v[180:183], v[12:15]
	v_mfma_f32_16x16x32_bf16 v[4:7], v[144:147], v[180:183], v[2:5]
	s_branch .LBB0_291

; #define PG8_STAGE(bufoff, gbase, voff) do { _Pragma("unroll") for (int _i = 0; _i < 2; ++_i) \
;         __builtin_amdgcn_global_load_lds((const unsigned*)((const char*)(gbase) + (voff)[_i]), (PG8_LAS unsigned*)(lds + (bufoff) + ldsw + _i * 8192), 16, 0, 0); } while (0)
; #define PG8_LDA(dst, b, h) do { _Pragma("unroll") for (int m = 0; m < 4; ++m) _Pragma("unroll") for (int k = 0; k < 2; ++k) dst[m][k] = *(const PG8_LAS bf16x8*)(lds + PG8_SA(b, h) + aoff + m * 2048 + k * 1024); } while (0)
; #define PG8_LDB(dst, b, h) do { _Pragma("unroll") for (int n = 0; n < 2; ++n) _Pragma("unroll") for (int k = 0; k < 2; ++k) dst[n][k] = *(const PG8_LAS bf16x8*)(lds + PG8_SB(b, h) + boff + n * 2048 + k * 1024); } while (0)
; #define PG8_MMA(ai, bj, At, Bt) do { __builtin_amdgcn_s_setprio(1); _Pragma("unroll") for (int m = 0; m < 4; ++m) _Pragma("unroll") for (int n = 0; n < 2; ++n) _Pragma("unroll") for (int k = 0; k < 2; ++k) \
;         acc[ai][bj][m][n] = __builtin_amdgcn_mfma_f32_16x16x32_bf16(Bt[n][k], At[m][k], acc[ai][bj][m][n], 0, 0, 0); __builtin_amdgcn_s_setprio(0); } while (0)
; #define PG8_WAIT_V(n) asm volatile("s_waitcnt vmcnt(" #n ")" ::: "memory")
; #define PG8_WAIT_L(n) asm volatile("s_waitcnt lgkmcnt(" #n ")" ::: "memory")
; #define PG8_BAR __builtin_amdgcn_s_barrier()
; #define PG8_SCHED __builtin_amdgcn_sched_barrier(0)
; template <class Epi, class Sched, bool ALIGN_EPI = false, bool SP2 = false>
; __device__ __forceinline__ void gemm_phase(PG8_LAS unsigned char* lds, const Gemm g, const Sched& S, const Epi& E) {
;     ...
;             const bool last = (t == nt - 2);
;             const char* a1 = cA + (size_t)(t + 1) * kstep;
;             const char* a2 = last ? nA : cA + (size_t)(t + 2) * kstep; const char* b2 = last ? nB : cB + (size_t)(t + 2) * kstep;
;             const char* a3 = a2 + kstep; const char* b3 = b2 + kstep;
;             if (last && has_next) S.a_ready(nxt);
;             if constexpr (SP2) {
;             PG8_LDB(B0, 0, 0); PG8_LDB(B1, 0, 1); PG8_SCHED; PG8_LDA(At, 0, 0); PG8_STAGE(PG8_SA(1, 1), a1 + hstep, voffA);
;             PG8_WAIT_V(8); PG8_WAIT_L(0); PG8_BAR; PG8_MMA(0, 0, At, B0); PG8_MMA(0, 1, At, B1); PG8_BAR; PG8_SCHED;
;             if (full) PG8_LDA(At, 0, 1); PG8_STAGE(PG8_SB(0, 0), b2, voffB); PG8_STAGE(PG8_SB(0, 1), b2 + hstep, voffB); PG8_STAGE(PG8_SA(0, 0), a2, voffA);
.LBB0_382:
	s_add_u32 s30, s24, s28
	s_addc_u32 s31, s25, s29
	s_add_u32 s30, s30, 0x100
	s_addc_u32 s31, s31, 0
	s_add_u32 s65, s62, s28
	s_addc_u32 s68, s63, s29
	s_add_i32 s69, 0, 0x10000
	s_cmpk_eq_i32 s28, 0x1500
	s_cselect_b32 s35, s27, s31
	s_cselect_b32 s34, s26, s30
	v_add_u32_e32 v146, s69, v140
	s_cselect_b32 s31, s9, s68
	s_cselect_b32 s30, s8, s65
	s_add_i32 s65, 0, 0x14000
	ds_read_b128 v[142:145], v146
	ds_read_b128 v[154:157], v146 offset:1024
	ds_read_b128 v[158:161], v146 offset:2048
	ds_read_b128 v[162:165], v146 offset:3072
	v_add_u32_e32 v146, s65, v140
	ds_read_b128 v[166:169], v146
	ds_read_b128 v[170:173], v146 offset:1024
	ds_read_b128 v[174:177], v146 offset:2048
	ds_read_b128 v[178:181], v146 offset:3072
	v_lshl_add_u64 v[146:147], v[136:137], 0, s[28:29]
	s_add_i32 m0, s44, 0xc000
	ds_read_b128 v[182:185], v141
	ds_read_b128 v[186:189], v141 offset:1024
	ds_read_b128 v[190:193], v141 offset:2048
	ds_read_b128 v[194:197], v141 offset:3072
	ds_read_b128 v[198:201], v141 offset:4096
	ds_read_b128 v[202:205], v141 offset:5120
	ds_read_b128 v[206:209], v141 offset:6144
	ds_read_b128 v[220:223], v141 offset:7168
	global_load_lds_dwordx4 v[146:147], off
	v_lshl_add_u64 v[146:147], v[138:139], 0, s[28:29]
	s_add_i32 m0, s44, 0xe000
	s_nop 0
	global_load_lds_dwordx4 v[146:147], off
	s_waitcnt vmcnt(8)
	s_waitcnt lgkmcnt(0)
	s_setprio 1
	s_barrier
	s_waitcnt lgkmcnt(0)
	v_mfma_f32_16x16x32_bf16 v[114:117], v[142:145], v[182:185], v[114:117]
	v_mfma_f32_16x16x32_bf16 v[82:85], v[158:161], v[182:185], v[82:85]
	v_mfma_f32_16x16x32_bf16 v[122:125], v[142:145], v[190:193], v[122:125]
	v_mfma_f32_16x16x32_bf16 v[94:97], v[158:161], v[190:193], v[94:97]
	v_mfma_f32_16x16x32_bf16 v[126:129], v[142:145], v[198:201], v[126:129]
	v_mfma_f32_16x16x32_bf16 v[106:109], v[158:161], v[198:201], v[106:109]
	v_mfma_f32_16x16x32_bf16 v[118:121], v[142:145], v[206:209], v[118:121]
	v_mfma_f32_16x16x32_bf16 v[110:113], v[158:161], v[206:209], v[110:113]
	v_mfma_f32_16x16x32_bf16 v[114:117], v[154:157], v[186:189], v[114:117]
	v_mfma_f32_16x16x32_bf16 v[82:85], v[162:165], v[186:189], v[82:85]
	v_mfma_f32_16x16x32_bf16 v[122:125], v[154:157], v[194:197], v[122:125]
	v_mfma_f32_16x16x32_bf16 v[94:97], v[162:165], v[194:197], v[94:97]
	v_mfma_f32_16x16x32_bf16 v[126:129], v[154:157], v[202:205], v[126:129]
	v_mfma_f32_16x16x32_bf16 v[106:109], v[162:165], v[202:205], v[106:109]
	v_mfma_f32_16x16x32_bf16 v[118:121], v[154:157], v[220:223], v[118:121]
	v_mfma_f32_16x16x32_bf16 v[110:113], v[162:165], v[220:223], v[110:113]
	v_mfma_f32_16x16x32_bf16 v[26:29], v[166:169], v[182:185], v[26:29]
	v_mfma_f32_16x16x32_bf16 v[2:5], v[174:177], v[182:185], v[2:5]
	v_mfma_f32_16x16x32_bf16 v[34:37], v[166:169], v[190:193], v[34:37]
	v_mfma_f32_16x16x32_bf16 v[6:9], v[174:177], v[190:193], v[6:9]
	v_mfma_f32_16x16x32_bf16 v[42:45], v[166:169], v[198:201], v[42:45]
	v_mfma_f32_16x16x32_bf16 v[10:13], v[174:177], v[198:201], v[10:13]
	v_mfma_f32_16x16x32_bf16 v[46:49], v[166:169], v[206:209], v[46:49]
	v_mfma_f32_16x16x32_bf16 v[14:17], v[174:177], v[206:209], v[14:17]
	v_mfma_f32_16x16x32_bf16 v[26:29], v[170:173], v[186:189], v[26:29]
	v_mfma_f32_16x16x32_bf16 v[2:5], v[178:181], v[186:189], v[2:5]
	v_mfma_f32_16x16x32_bf16 v[34:37], v[170:173], v[194:197], v[34:37]
	v_mfma_f32_16x16x32_bf16 v[6:9], v[178:181], v[194:197], v[6:9]
	v_mfma_f32_16x16x32_bf16 v[42:45], v[170:173], v[202:205], v[42:45]
	v_mfma_f32_16x16x32_bf16 v[10:13], v[178:181], v[202:205], v[10:13]
	v_mfma_f32_16x16x32_bf16 v[46:49], v[170:173], v[220:223], v[46:49]
	v_mfma_f32_16x16x32_bf16 v[14:17], v[178:181], v[220:223], v[14:17]
	s_barrier
	s_setprio 0
	s_add_i32 s68, s69, s43
	v_lshl_add_u64 v[146:147], s[30:31], 0, v[0:1]
	s_mov_b32 m0, s68
	ds_read_b128 v[182:185], v141 offset:16384
	ds_read_b128 v[186:189], v141 offset:17408
	ds_read_b128 v[190:193], v141 offset:18432
	ds_read_b128 v[194:197], v141 offset:19456
	ds_read_b128 v[198:201], v141 offset:20480
	ds_read_b128 v[202:205], v141 offset:21504
	ds_read_b128 v[206:209], v141 offset:22528
	ds_read_b128 v[220:223], v141 offset:23552
	global_load_lds_dwordx4 v[146:147], off
	s_add_i32 m0, s68, 0x2000
	s_add_u32 s68, s30, 0xb0000
	v_lshl_add_u64 v[150:151], s[30:31], 0, v[130:131]
	s_addc_u32 s69, s31, 0
	s_add_i32 s65, s65, s43
	global_load_lds_dwordx4 v[150:151], off
	v_lshl_add_u64 v[210:211], s[68:69], 0, v[0:1]
	s_mov_b32 m0, s65
	v_lshl_add_u64 v[212:213], s[34:35], 0, v[130:131]
	global_load_lds_dwordx4 v[210:211], off
	v_lshl_add_u64 v[210:211], s[68:69], 0, v[130:131]
	s_add_i32 m0, s65, 0x2000
	s_nop 0
	global_load_lds_dwordx4 v[210:211], off
	v_lshl_add_u64 v[210:211], s[34:35], 0, v[0:1]
	s_mov_b32 m0, s44
	s_nop 0
	global_load_lds_dwordx4 v[210:211], off
	s_mov_b32 m0, s45
	s_nop 0
	global_load_lds_dwordx4 v[212:213], off
	s_waitcnt vmcnt(8)
	s_waitcnt lgkmcnt(0)
	s_setprio 1
	s_barrier
; #define PG8_STAGE(bufoff, gbase, voff) do { _Pragma("unroll") for (int _i = 0; _i < 2; ++_i) \
;         __builtin_amdgcn_global_load_lds((const unsigned*)((const char*)(gbase) + (voff)[_i]), (PG8_LAS unsigned*)(lds + (bufoff) + ldsw + _i * 8192), 16, 0, 0); } while (0)
; #define PG8_LDA(dst, b, h) do { _Pragma("unroll") for (int m = 0; m < 4; ++m) _Pragma("unroll") for (int k = 0; k < 2; ++k) dst[m][k] = *(const PG8_LAS bf16x8*)(lds + PG8_SA(b, h) + aoff + m * 2048 + k * 1024); } while (0)
; #define PG8_LDB(dst, b, h) do { _Pragma("unroll") for (int n = 0; n < 2; ++n) _Pragma("unroll") for (int k = 0; k < 2; ++k) dst[n][k] = *(const PG8_LAS bf16x8*)(lds + PG8_SB(b, h) + boff + n * 2048 + k * 1024); } while (0)
; #define PG8_MMA(ai, bj, At, Bt) do { __builtin_amdgcn_s_setprio(1); _Pragma("unroll") for (int m = 0; m < 4; ++m) _Pragma("unroll") for (int n = 0; n < 2; ++n) _Pragma("unroll") for (int k = 0; k < 2; ++k) \
;         acc[ai][bj][m][n] = __builtin_amdgcn_mfma_f32_16x16x32_bf16(Bt[n][k], At[m][k], acc[ai][bj][m][n], 0, 0, 0); __builtin_amdgcn_s_setprio(0); } while (0)
; #define PG8_WAIT_V(n) asm volatile("s_waitcnt vmcnt(" #n ")" ::: "memory")
; #define PG8_WAIT_L(n) asm volatile("s_waitcnt lgkmcnt(" #n ")" ::: "memory")
; #define PG8_BAR __builtin_amdgcn_s_barrier()
; #define PG8_SCHED __builtin_amdgcn_sched_barrier(0)
; template <class Epi, class Sched, bool ALIGN_EPI = false, bool SP2 = false>
; __device__ __forceinline__ void gemm_phase(PG8_LAS unsigned char* lds, const Gemm g, const Sched& S, const Epi& E) {
;     ...
;             PG8_WAIT_V(8); PG8_WAIT_L(0); PG8_BAR; if (full) { PG8_MMA(1, 0, At, B0); PG8_MMA(1, 1, At, B1); } PG8_BAR; PG8_SCHED;
;             PG8_LDB(B0, 1, 0); PG8_LDB(B1, 1, 1); PG8_SCHED; PG8_LDA(At, 1, 0); PG8_STAGE(PG8_SA(0, 1), a2 + hstep, voffA);
;             PG8_WAIT_V(8); PG8_WAIT_L(0); PG8_BAR; PG8_MMA(0, 0, At, B0); PG8_MMA(0, 1, At, B1); PG8_BAR; PG8_SCHED;
	s_waitcnt lgkmcnt(0)
	v_mfma_f32_16x16x32_bf16 v[102:105], v[142:145], v[182:185], v[102:105]
	v_mfma_f32_16x16x32_bf16 v[98:101], v[158:161], v[182:185], v[98:101]
	v_mfma_f32_16x16x32_bf16 v[90:93], v[142:145], v[190:193], v[90:93]
	v_mfma_f32_16x16x32_bf16 v[86:89], v[158:161], v[190:193], v[86:89]
	v_mfma_f32_16x16x32_bf16 v[78:81], v[142:145], v[198:201], v[78:81]
	v_mfma_f32_16x16x32_bf16 v[74:77], v[158:161], v[198:201], v[74:77]
	v_mfma_f32_16x16x32_bf16 v[70:73], v[142:145], v[206:209], v[70:73]
	v_mfma_f32_16x16x32_bf16 v[66:69], v[158:161], v[206:209], v[66:69]
	v_mfma_f32_16x16x32_bf16 v[102:105], v[154:157], v[186:189], v[102:105]
	v_mfma_f32_16x16x32_bf16 v[98:101], v[162:165], v[186:189], v[98:101]
	v_mfma_f32_16x16x32_bf16 v[90:93], v[154:157], v[194:197], v[90:93]
	v_mfma_f32_16x16x32_bf16 v[86:89], v[162:165], v[194:197], v[86:89]
	v_mfma_f32_16x16x32_bf16 v[78:81], v[154:157], v[202:205], v[78:81]
	v_mfma_f32_16x16x32_bf16 v[74:77], v[162:165], v[202:205], v[74:77]
	v_mfma_f32_16x16x32_bf16 v[70:73], v[154:157], v[220:223], v[70:73]
	v_mfma_f32_16x16x32_bf16 v[66:69], v[162:165], v[220:223], v[66:69]
	v_mfma_f32_16x16x32_bf16 v[54:57], v[166:169], v[182:185], v[54:57]
	v_mfma_f32_16x16x32_bf16 v[18:21], v[174:177], v[182:185], v[18:21]
	v_mfma_f32_16x16x32_bf16 v[58:61], v[166:169], v[190:193], v[58:61]
	v_mfma_f32_16x16x32_bf16 v[30:33], v[174:177], v[190:193], v[30:33]
	v_mfma_f32_16x16x32_bf16 v[62:65], v[166:169], v[198:201], v[62:65]
	v_mfma_f32_16x16x32_bf16 v[38:41], v[174:177], v[198:201], v[38:41]
	v_mfma_f32_16x16x32_bf16 v[50:53], v[166:169], v[206:209], v[50:53]
	v_mfma_f32_16x16x32_bf16 v[22:25], v[174:177], v[206:209], v[22:25]
	v_mfma_f32_16x16x32_bf16 v[54:57], v[170:173], v[186:189], v[54:57]
	v_mfma_f32_16x16x32_bf16 v[18:21], v[178:181], v[186:189], v[18:21]
	v_mfma_f32_16x16x32_bf16 v[58:61], v[170:173], v[194:197], v[58:61]
	v_mfma_f32_16x16x32_bf16 v[30:33], v[178:181], v[194:197], v[30:33]
	v_mfma_f32_16x16x32_bf16 v[62:65], v[170:173], v[202:205], v[62:65]
	v_mfma_f32_16x16x32_bf16 v[38:41], v[178:181], v[202:205], v[38:41]
	v_mfma_f32_16x16x32_bf16 v[50:53], v[170:173], v[220:223], v[50:53]
	v_mfma_f32_16x16x32_bf16 v[22:25], v[178:181], v[220:223], v[22:25]
	s_barrier
	s_setprio 0
	s_add_i32 s65, 0, 0x18000
	v_add_u32_e32 v149, s65, v140
	s_add_i32 s68, 0, 0x1c000
	ds_read_b128 v[142:145], v149
	ds_read_b128 v[154:157], v149 offset:1024
	ds_read_b128 v[158:161], v149 offset:2048
	ds_read_b128 v[162:165], v149 offset:3072
	v_add_u32_e32 v149, s68, v140
	ds_read_b128 v[166:169], v149
	ds_read_b128 v[170:173], v149 offset:1024
	ds_read_b128 v[174:177], v149 offset:2048
	ds_read_b128 v[178:181], v149 offset:3072
	s_add_u32 s34, s34, 0xb0000
	s_addc_u32 s35, s35, 0
	s_mov_b32 m0, s48
	v_lshl_add_u64 v[214:215], s[34:35], 0, v[0:1]
	ds_read_b128 v[182:185], v141 offset:32768
	ds_read_b128 v[186:189], v141 offset:33792
	ds_read_b128 v[190:193], v141 offset:34816
	ds_read_b128 v[194:197], v141 offset:35840
	ds_read_b128 v[198:201], v141 offset:36864
	ds_read_b128 v[202:205], v141 offset:37888
	ds_read_b128 v[206:209], v141 offset:38912
	ds_read_b128 v[220:223], v141 offset:39936
	global_load_lds_dwordx4 v[214:215], off
	v_lshl_add_u64 v[214:215], s[34:35], 0, v[130:131]
	s_mov_b32 m0, s54
	s_nop 0
	global_load_lds_dwordx4 v[214:215], off
	s_waitcnt vmcnt(8)
	s_waitcnt lgkmcnt(0)
	s_setprio 1
	s_barrier
	s_waitcnt lgkmcnt(0)
	v_mfma_f32_16x16x32_bf16 v[114:117], v[142:145], v[182:185], v[114:117]
	v_mfma_f32_16x16x32_bf16 v[82:85], v[158:161], v[182:185], v[82:85]
	v_mfma_f32_16x16x32_bf16 v[122:125], v[142:145], v[190:193], v[122:125]
	v_mfma_f32_16x16x32_bf16 v[94:97], v[158:161], v[190:193], v[94:97]
	v_mfma_f32_16x16x32_bf16 v[126:129], v[142:145], v[198:201], v[126:129]
	v_mfma_f32_16x16x32_bf16 v[106:109], v[158:161], v[198:201], v[106:109]
	v_mfma_f32_16x16x32_bf16 v[118:121], v[142:145], v[206:209], v[118:121]
	v_mfma_f32_16x16x32_bf16 v[110:113], v[158:161], v[206:209], v[110:113]
	v_mfma_f32_16x16x32_bf16 v[114:117], v[154:157], v[186:189], v[114:117]
	v_mfma_f32_16x16x32_bf16 v[82:85], v[162:165], v[186:189], v[82:85]
	v_mfma_f32_16x16x32_bf16 v[122:125], v[154:157], v[194:197], v[122:125]
	v_mfma_f32_16x16x32_bf16 v[94:97], v[162:165], v[194:197], v[94:97]
	v_mfma_f32_16x16x32_bf16 v[126:129], v[154:157], v[202:205], v[126:129]
	v_mfma_f32_16x16x32_bf16 v[106:109], v[162:165], v[202:205], v[106:109]
	v_mfma_f32_16x16x32_bf16 v[118:121], v[154:157], v[220:223], v[118:121]
	v_mfma_f32_16x16x32_bf16 v[110:113], v[162:165], v[220:223], v[110:113]
	v_mfma_f32_16x16x32_bf16 v[26:29], v[166:169], v[182:185], v[26:29]
	v_mfma_f32_16x16x32_bf16 v[2:5], v[174:177], v[182:185], v[2:5]
	v_mfma_f32_16x16x32_bf16 v[34:37], v[166:169], v[190:193], v[34:37]
	v_mfma_f32_16x16x32_bf16 v[6:9], v[174:177], v[190:193], v[6:9]
	v_mfma_f32_16x16x32_bf16 v[42:45], v[166:169], v[198:201], v[42:45]
	v_mfma_f32_16x16x32_bf16 v[10:13], v[174:177], v[198:201], v[10:13]
	v_mfma_f32_16x16x32_bf16 v[46:49], v[166:169], v[206:209], v[46:49]
	v_mfma_f32_16x16x32_bf16 v[14:17], v[174:177], v[206:209], v[14:17]
	v_mfma_f32_16x16x32_bf16 v[26:29], v[170:173], v[186:189], v[26:29]
	v_mfma_f32_16x16x32_bf16 v[2:5], v[178:181], v[186:189], v[2:5]
	v_mfma_f32_16x16x32_bf16 v[34:37], v[170:173], v[194:197], v[34:37]
	v_mfma_f32_16x16x32_bf16 v[6:9], v[178:181], v[194:197], v[6:9]
	v_mfma_f32_16x16x32_bf16 v[42:45], v[170:173], v[202:205], v[42:45]
	v_mfma_f32_16x16x32_bf16 v[10:13], v[178:181], v[202:205], v[10:13]
	v_mfma_f32_16x16x32_bf16 v[46:49], v[170:173], v[220:223], v[46:49]
	v_mfma_f32_16x16x32_bf16 v[14:17], v[178:181], v[220:223], v[14:17]
	s_barrier
; #define PG8_STAGE(bufoff, gbase, voff) do { _Pragma("unroll") for (int _i = 0; _i < 2; ++_i) \
;         __builtin_amdgcn_global_load_lds((const unsigned*)((const char*)(gbase) + (voff)[_i]), (PG8_LAS unsigned*)(lds + (bufoff) + ldsw + _i * 8192), 16, 0, 0); } while (0)
; #define PG8_LDA(dst, b, h) do { _Pragma("unroll") for (int m = 0; m < 4; ++m) _Pragma("unroll") for (int k = 0; k < 2; ++k) dst[m][k] = *(const PG8_LAS bf16x8*)(lds + PG8_SA(b, h) + aoff + m * 2048 + k * 1024); } while (0)
; #define PG8_MMA(ai, bj, At, Bt) do { __builtin_amdgcn_s_setprio(1); _Pragma("unroll") for (int m = 0; m < 4; ++m) _Pragma("unroll") for (int n = 0; n < 2; ++n) _Pragma("unroll") for (int k = 0; k < 2; ++k) \
;         acc[ai][bj][m][n] = __builtin_amdgcn_mfma_f32_16x16x32_bf16(Bt[n][k], At[m][k], acc[ai][bj][m][n], 0, 0, 0); __builtin_amdgcn_s_setprio(0); } while (0)
; #define PG8_WAIT_V(n) asm volatile("s_waitcnt vmcnt(" #n ")" ::: "memory")
; #define PG8_WAIT_L(n) asm volatile("s_waitcnt lgkmcnt(" #n ")" ::: "memory")
; #define PG8_BAR __builtin_amdgcn_s_barrier()
; #define PG8_SCHED __builtin_amdgcn_sched_barrier(0)
; template <class Epi, class Sched, bool ALIGN_EPI = false, bool SP2 = false>
; __device__ __forceinline__ void gemm_phase(PG8_LAS unsigned char* lds, const Gemm g, const Sched& S, const Epi& E) {
;     ...
;             if (full) PG8_LDA(At, 1, 1); PG8_STAGE(PG8_SB(1, 0), b3, voffB); PG8_STAGE(PG8_SB(1, 1), b3 + hstep, voffB); PG8_STAGE(PG8_SA(1, 0), a3, voffA);
;             PG8_WAIT_V(8); PG8_WAIT_L(0); PG8_BAR; if (full) { PG8_MMA(1, 0, At, B0); PG8_MMA(1, 1, At, B1); } PG8_BAR; PG8_SCHED;
;     ...
;         if (!Sched::KEEP || (nxt.pn >> 2) == 0) {
; #pragma unroll
;         for (int a = 0; a < 2; ++a)
; #pragma unroll
;             for (int b = 0; b < 2; ++b)
; #pragma unroll
;                 for (int m = 0; m < 4; ++m)
; #pragma unroll
;                     for (int n = 0; n < 2; ++n) acc[a][b][m][n] = (f32x4){0.f, 0.f, 0.f, 0.f};
;         }
	s_setprio 0
	s_add_i32 s34, s65, s43
	v_lshl_add_u64 v[146:147], v[146:147], 0, s[52:53]
	s_mov_b32 m0, s34
	ds_read_b128 v[182:185], v141 offset:49152
	ds_read_b128 v[186:189], v141 offset:50176
	ds_read_b128 v[190:193], v141 offset:51200
	ds_read_b128 v[194:197], v141 offset:52224
	ds_read_b128 v[198:201], v141 offset:53248
	ds_read_b128 v[202:205], v141 offset:54272
	ds_read_b128 v[206:209], v141 offset:55296
	ds_read_b128 v[220:223], v141 offset:56320
	global_load_lds_dwordx4 v[146:147], off
	s_add_i32 m0, s34, 0x2000
	s_add_u32 s30, s30, 0xb0080
	v_lshl_add_u64 v[146:147], v[150:151], 0, s[52:53]
	s_addc_u32 s31, s31, 0
	s_add_i32 s34, s68, s43
	global_load_lds_dwordx4 v[146:147], off
	v_lshl_add_u64 v[146:147], s[30:31], 0, v[0:1]
	s_mov_b32 m0, s34
	s_nop 0
	global_load_lds_dwordx4 v[146:147], off
	v_lshl_add_u64 v[146:147], s[30:31], 0, v[130:131]
	s_add_i32 m0, s34, 0x2000
	s_nop 0
	global_load_lds_dwordx4 v[146:147], off
	v_lshl_add_u64 v[146:147], v[210:211], 0, s[52:53]
	s_mov_b32 m0, s55
	s_nop 0
	global_load_lds_dwordx4 v[146:147], off
	v_lshl_add_u64 v[146:147], v[212:213], 0, s[52:53]
	s_mov_b32 m0, s56
	s_nop 0
	global_load_lds_dwordx4 v[146:147], off
	s_waitcnt vmcnt(8)
	s_waitcnt lgkmcnt(0)
	s_setprio 1
	s_barrier
	s_waitcnt lgkmcnt(0)
	v_mfma_f32_16x16x32_bf16 v[102:105], v[142:145], v[182:185], v[102:105]
	v_mfma_f32_16x16x32_bf16 v[98:101], v[158:161], v[182:185], v[98:101]
	v_mfma_f32_16x16x32_bf16 v[90:93], v[142:145], v[190:193], v[90:93]
	v_mfma_f32_16x16x32_bf16 v[86:89], v[158:161], v[190:193], v[86:89]
	v_mfma_f32_16x16x32_bf16 v[78:81], v[142:145], v[198:201], v[78:81]
	v_mfma_f32_16x16x32_bf16 v[74:77], v[158:161], v[198:201], v[74:77]
	v_mfma_f32_16x16x32_bf16 v[70:73], v[142:145], v[206:209], v[70:73]
	v_mfma_f32_16x16x32_bf16 v[66:69], v[158:161], v[206:209], v[66:69]
	v_mfma_f32_16x16x32_bf16 v[102:105], v[154:157], v[186:189], v[102:105]
	v_mfma_f32_16x16x32_bf16 v[98:101], v[162:165], v[186:189], v[98:101]
	v_mfma_f32_16x16x32_bf16 v[90:93], v[154:157], v[194:197], v[90:93]
	v_mfma_f32_16x16x32_bf16 v[86:89], v[162:165], v[194:197], v[86:89]
	v_mfma_f32_16x16x32_bf16 v[78:81], v[154:157], v[202:205], v[78:81]
	v_mfma_f32_16x16x32_bf16 v[74:77], v[162:165], v[202:205], v[74:77]
	v_mfma_f32_16x16x32_bf16 v[70:73], v[154:157], v[220:223], v[70:73]
	v_mfma_f32_16x16x32_bf16 v[66:69], v[162:165], v[220:223], v[66:69]
	v_mfma_f32_16x16x32_bf16 v[54:57], v[166:169], v[182:185], v[54:57]
	v_mfma_f32_16x16x32_bf16 v[18:21], v[174:177], v[182:185], v[18:21]
	v_mfma_f32_16x16x32_bf16 v[58:61], v[166:169], v[190:193], v[58:61]
	v_mfma_f32_16x16x32_bf16 v[30:33], v[174:177], v[190:193], v[30:33]
	v_mfma_f32_16x16x32_bf16 v[62:65], v[166:169], v[198:201], v[62:65]
	v_mfma_f32_16x16x32_bf16 v[38:41], v[174:177], v[198:201], v[38:41]
	v_mfma_f32_16x16x32_bf16 v[50:53], v[166:169], v[206:209], v[50:53]
	v_mfma_f32_16x16x32_bf16 v[22:25], v[174:177], v[206:209], v[22:25]
	v_mfma_f32_16x16x32_bf16 v[54:57], v[170:173], v[186:189], v[54:57]
	v_mfma_f32_16x16x32_bf16 v[18:21], v[178:181], v[186:189], v[18:21]
	v_mfma_f32_16x16x32_bf16 v[58:61], v[170:173], v[194:197], v[58:61]
	v_mfma_f32_16x16x32_bf16 v[30:33], v[178:181], v[194:197], v[30:33]
	v_mfma_f32_16x16x32_bf16 v[62:65], v[170:173], v[202:205], v[62:65]
	v_mfma_f32_16x16x32_bf16 v[38:41], v[178:181], v[202:205], v[38:41]
	v_mfma_f32_16x16x32_bf16 v[50:53], v[170:173], v[220:223], v[50:53]
	v_mfma_f32_16x16x32_bf16 v[22:25], v[178:181], v[220:223], v[22:25]
	s_barrier
	s_setprio 0
	s_add_i32 s64, s64, 2
	s_add_u32 s28, s28, 0x100
	s_addc_u32 s29, s29, 0
	s_cmp_gt_u32 s64, 41
	s_cbranch_scc0 .LBB0_382
	s_add_u32 s28, s62, 0xffffff00
	s_addc_u32 s29, s63, -1
	s_and_b64 vcc, exec, s[6:7]
	s_cbranch_vccnz .LBB0_369
	v_mov_b32_e32 v22, 0
	s_mov_b32 s18, s59
	s_mov_b32 s37, s60
	s_mov_b64 s[24:25], s[26:27]
	s_mov_b32 s58, s61
	v_mov_b32_e32 v23, v22
	v_mov_b32_e32 v24, v22
	v_mov_b32_e32 v25, v22
	v_mov_b32_e32 v50, v22
	v_mov_b32_e32 v51, v22
	v_mov_b32_e32 v52, v22
	v_mov_b32_e32 v53, v22
	v_mov_b32_e32 v38, v22
	v_mov_b32_e32 v39, v22
	v_mov_b32_e32 v40, v22
	v_mov_b32_e32 v41, v22
	v_mov_b32_e32 v62, v22
	v_mov_b32_e32 v63, v22
	v_mov_b32_e32 v64, v22
	v_mov_b32_e32 v65, v22
	v_mov_b32_e32 v30, v22
	v_mov_b32_e32 v31, v22
	v_mov_b32_e32 v32, v22
	v_mov_b32_e32 v33, v22
	v_mov_b32_e32 v58, v22
	v_mov_b32_e32 v59, v22
	v_mov_b32_e32 v60, v22
	v_mov_b32_e32 v61, v22
	v_mov_b32_e32 v18, v22
	v_mov_b32_e32 v19, v22
	v_mov_b32_e32 v20, v22
	v_mov_b32_e32 v21, v22
	v_mov_b32_e32 v54, v22
	v_mov_b32_e32 v55, v22
	v_mov_b32_e32 v56, v22
	v_mov_b32_e32 v57, v22
	v_mov_b32_e32 v66, v22
	v_mov_b32_e32 v67, v22
	v_mov_b32_e32 v68, v22
	v_mov_b32_e32 v69, v22
	v_mov_b32_e32 v70, v22
	v_mov_b32_e32 v71, v22
	v_mov_b32_e32 v72, v22
	v_mov_b32_e32 v73, v22
	v_mov_b32_e32 v74, v22
	v_mov_b32_e32 v75, v22
	v_mov_b32_e32 v76, v22
	v_mov_b32_e32 v77, v22
	v_mov_b32_e32 v78, v22
	v_mov_b32_e32 v79, v22
	v_mov_b32_e32 v80, v22
	v_mov_b32_e32 v81, v22
	v_mov_b32_e32 v86, v22
	v_mov_b32_e32 v87, v22
	v_mov_b32_e32 v88, v22
	v_mov_b32_e32 v89, v22
	v_mov_b32_e32 v90, v22
	v_mov_b32_e32 v91, v22
	v_mov_b32_e32 v92, v22
	v_mov_b32_e32 v93, v22
	v_mov_b32_e32 v98, v22
	v_mov_b32_e32 v99, v22
	v_mov_b32_e32 v100, v22
	v_mov_b32_e32 v101, v22
	v_mov_b32_e32 v102, v22
	v_mov_b32_e32 v103, v22
	v_mov_b32_e32 v104, v22
	v_mov_b32_e32 v105, v22
	v_mov_b32_e32 v14, v22
	v_mov_b32_e32 v15, v22
	v_mov_b32_e32 v16, v22
	v_mov_b32_e32 v17, v22
	v_mov_b32_e32 v46, v22
	v_mov_b32_e32 v47, v22
	v_mov_b32_e32 v48, v22
	v_mov_b32_e32 v49, v22
	v_mov_b32_e32 v10, v22
	v_mov_b32_e32 v11, v22
	v_mov_b32_e32 v12, v22
	v_mov_b32_e32 v13, v22
	v_mov_b32_e32 v42, v22
	v_mov_b32_e32 v43, v22
	v_mov_b32_e32 v44, v22
	v_mov_b32_e32 v45, v22
	v_mov_b32_e32 v6, v22
	v_mov_b32_e32 v7, v22
	v_mov_b32_e32 v8, v22
	v_mov_b32_e32 v9, v22
	v_mov_b32_e32 v34, v22
	v_mov_b32_e32 v35, v22
	v_mov_b32_e32 v36, v22
	v_mov_b32_e32 v37, v22
	v_mov_b32_e32 v2, v22
	v_mov_b32_e32 v3, v22
	v_mov_b32_e32 v4, v22
	v_mov_b32_e32 v5, v22
	v_mov_b32_e32 v26, v22
	v_mov_b32_e32 v27, v22
	v_mov_b32_e32 v28, v22
	v_mov_b32_e32 v29, v22
	v_mov_b32_e32 v110, v22
	v_mov_b32_e32 v111, v22
	v_mov_b32_e32 v112, v22
	v_mov_b32_e32 v113, v22
	v_mov_b32_e32 v118, v22
	v_mov_b32_e32 v119, v22
	v_mov_b32_e32 v120, v22
	v_mov_b32_e32 v121, v22
	v_mov_b32_e32 v106, v22
	v_mov_b32_e32 v107, v22
	v_mov_b32_e32 v108, v22
	v_mov_b32_e32 v109, v22
	v_mov_b32_e32 v126, v22
	v_mov_b32_e32 v127, v22
	v_mov_b32_e32 v128, v22
	v_mov_b32_e32 v129, v22
	v_mov_b32_e32 v94, v22
	v_mov_b32_e32 v95, v22
	v_mov_b32_e32 v96, v22
	v_mov_b32_e32 v97, v22
	v_mov_b32_e32 v122, v22
	v_mov_b32_e32 v123, v22
	v_mov_b32_e32 v124, v22
	v_mov_b32_e32 v125, v22
	v_mov_b32_e32 v82, v22
	v_mov_b32_e32 v83, v22
	v_mov_b32_e32 v84, v22
	v_mov_b32_e32 v85, v22
	v_mov_b32_e32 v114, v22
	v_mov_b32_e32 v115, v22
	v_mov_b32_e32 v116, v22
	v_mov_b32_e32 v117, v22
	s_andn2_b64 vcc, exec, s[4:5]
	s_cbranch_vccnz .LBB0_370

; #define PG8_STAGE(bufoff, gbase, voff) do { _Pragma("unroll") for (int _i = 0; _i < 2; ++_i) \
;         __builtin_amdgcn_global_load_lds((const unsigned*)((const char*)(gbase) + (voff)[_i]), (PG8_LAS unsigned*)(lds + (bufoff) + ldsw + _i * 8192), 16, 0, 0); } while (0)
; #define PG8_LDA(dst, b, h) do { _Pragma("unroll") for (int m = 0; m < 4; ++m) _Pragma("unroll") for (int k = 0; k < 2; ++k) dst[m][k] = *(const PG8_LAS bf16x8*)(lds + PG8_SA(b, h) + aoff + m * 2048 + k * 1024); } while (0)
; #define PG8_LDB(dst, b, h) do { _Pragma("unroll") for (int n = 0; n < 2; ++n) _Pragma("unroll") for (int k = 0; k < 2; ++k) dst[n][k] = *(const PG8_LAS bf16x8*)(lds + PG8_SB(b, h) + boff + n * 2048 + k * 1024); } while (0)
; #define PG8_MMA(ai, bj, At, Bt) do { __builtin_amdgcn_s_setprio(1); _Pragma("unroll") for (int m = 0; m < 4; ++m) _Pragma("unroll") for (int n = 0; n < 2; ++n) _Pragma("unroll") for (int k = 0; k < 2; ++k) \
;         acc[ai][bj][m][n] = __builtin_amdgcn_mfma_f32_16x16x32_bf16(Bt[n][k], At[m][k], acc[ai][bj][m][n], 0, 0, 0); __builtin_amdgcn_s_setprio(0); } while (0)
; #define PG8_WAIT_V(n) asm volatile("s_waitcnt vmcnt(" #n ")" ::: "memory")
; #define PG8_WAIT_L(n) asm volatile("s_waitcnt lgkmcnt(" #n ")" ::: "memory")
; #define PG8_BAR __builtin_amdgcn_s_barrier()
; #define PG8_SCHED __builtin_amdgcn_sched_barrier(0)
; template <class Epi, class Sched, bool ALIGN_EPI = false, bool SP2 = false>
; __device__ __forceinline__ void gemm_phase(PG8_LAS unsigned char* lds, const Gemm g, const Sched& S, const Epi& E) {
;     ...
;             const bool last = (t == nt - 2);
;             const char* a1 = cA + (size_t)(t + 1) * kstep;
;             const char* a2 = last ? nA : cA + (size_t)(t + 2) * kstep; const char* b2 = last ? nB : cB + (size_t)(t + 2) * kstep;
;             const char* a3 = a2 + kstep; const char* b3 = b2 + kstep;
;             if (last && has_next) S.a_ready(nxt);
;             if constexpr (SP2) {
;             PG8_LDB(B0, 0, 0); PG8_LDB(B1, 0, 1); PG8_SCHED; PG8_LDA(At, 0, 0); PG8_STAGE(PG8_SA(1, 1), a1 + hstep, voffA);
;             PG8_WAIT_V(8); PG8_WAIT_L(0); PG8_BAR; PG8_MMA(0, 0, At, B0); PG8_MMA(0, 1, At, B1); PG8_BAR; PG8_SCHED;
;             if (full) PG8_LDA(At, 0, 1); PG8_STAGE(PG8_SB(0, 0), b2, voffB); PG8_STAGE(PG8_SB(0, 1), b2 + hstep, voffB); PG8_STAGE(PG8_SA(0, 0), a2, voffA);
.LBB0_521:
	v_add_u32_e32 v0, 0x10000, v225
	ds_read_b128 v[148:151], v0
	ds_read_b128 v[152:155], v0 offset:1024
	ds_read_b128 v[156:159], v0 offset:2048
	ds_read_b128 v[160:163], v0 offset:3072
	v_add_u32_e32 v0, 0x14000, v225
	ds_read_b128 v[132:135], v0
	ds_read_b128 v[136:139], v0 offset:1024
	ds_read_b128 v[140:143], v0 offset:2048
	ds_read_b128 v[144:147], v0 offset:3072
	v_lshl_add_u64 v[2:3], s[34:35], 0, v[204:205]
	s_add_i32 m0, s27, 0xc000
	ds_read_b128 v[176:179], v241
	ds_read_b128 v[192:195], v241 offset:1024
	ds_read_b128 v[172:175], v241 offset:2048
	ds_read_b128 v[188:191], v241 offset:3072
	ds_read_b128 v[168:171], v241 offset:4096
	ds_read_b128 v[184:187], v241 offset:5120
	ds_read_b128 v[164:167], v241 offset:6144
	ds_read_b128 v[180:183], v241 offset:7168
	global_load_lds_dwordx4 v[2:3], off
	v_lshl_add_u64 v[2:3], s[34:35], 0, v[206:207]
	s_add_i32 m0, s27, 0xe000
	s_nop 0
	global_load_lds_dwordx4 v[2:3], off
	s_waitcnt vmcnt(8)
	s_waitcnt lgkmcnt(0)
	s_setprio 1
	s_barrier
	s_waitcnt lgkmcnt(0)
	v_mfma_f32_16x16x32_bf16 v[128:131], v[148:151], v[176:179], v[128:131]
	v_mfma_f32_16x16x32_bf16 v[124:127], v[156:159], v[176:179], v[124:127]
	v_mfma_f32_16x16x32_bf16 v[112:115], v[148:151], v[172:175], v[112:115]
	v_mfma_f32_16x16x32_bf16 v[108:111], v[156:159], v[172:175], v[108:111]
	v_mfma_f32_16x16x32_bf16 v[96:99], v[148:151], v[168:171], v[96:99]
	v_mfma_f32_16x16x32_bf16 v[92:95], v[156:159], v[168:171], v[92:95]
	v_mfma_f32_16x16x32_bf16 v[80:83], v[148:151], v[164:167], v[80:83]
	v_mfma_f32_16x16x32_bf16 v[76:79], v[156:159], v[164:167], v[76:79]
	v_mfma_f32_16x16x32_bf16 v[128:131], v[152:155], v[192:195], v[128:131]
	v_mfma_f32_16x16x32_bf16 v[124:127], v[160:163], v[192:195], v[124:127]
	v_mfma_f32_16x16x32_bf16 v[112:115], v[152:155], v[188:191], v[112:115]
	v_mfma_f32_16x16x32_bf16 v[108:111], v[160:163], v[188:191], v[108:111]
	v_mfma_f32_16x16x32_bf16 v[96:99], v[152:155], v[184:187], v[96:99]
	v_mfma_f32_16x16x32_bf16 v[92:95], v[160:163], v[184:187], v[92:95]
	v_mfma_f32_16x16x32_bf16 v[80:83], v[152:155], v[180:183], v[80:83]
	v_mfma_f32_16x16x32_bf16 v[76:79], v[160:163], v[180:183], v[76:79]
	v_mfma_f32_16x16x32_bf16 v[120:123], v[132:135], v[176:179], v[120:123]
	v_mfma_f32_16x16x32_bf16 v[116:119], v[140:143], v[176:179], v[116:119]
	v_mfma_f32_16x16x32_bf16 v[104:107], v[132:135], v[172:175], v[104:107]
	v_mfma_f32_16x16x32_bf16 v[100:103], v[140:143], v[172:175], v[100:103]
	v_mfma_f32_16x16x32_bf16 v[88:91], v[132:135], v[168:171], v[88:91]
	v_mfma_f32_16x16x32_bf16 v[84:87], v[140:143], v[168:171], v[84:87]
	v_mfma_f32_16x16x32_bf16 v[72:75], v[132:135], v[164:167], v[72:75]
	v_mfma_f32_16x16x32_bf16 v[68:71], v[140:143], v[164:167], v[68:71]
	v_mfma_f32_16x16x32_bf16 v[120:123], v[136:139], v[192:195], v[120:123]
	v_mfma_f32_16x16x32_bf16 v[116:119], v[144:147], v[192:195], v[116:119]
	v_mfma_f32_16x16x32_bf16 v[104:107], v[136:139], v[188:191], v[104:107]
	v_mfma_f32_16x16x32_bf16 v[100:103], v[144:147], v[188:191], v[100:103]
	v_mfma_f32_16x16x32_bf16 v[88:91], v[136:139], v[184:187], v[88:91]
	v_mfma_f32_16x16x32_bf16 v[84:87], v[144:147], v[184:187], v[84:87]
	v_mfma_f32_16x16x32_bf16 v[72:75], v[136:139], v[180:183], v[72:75]
	v_mfma_f32_16x16x32_bf16 v[68:71], v[144:147], v[180:183], v[68:71]
	s_barrier
	s_setprio 0
	v_cndmask_b32_e64 v0, 0, 1, s[30:31]
	v_cmp_ne_u32_e64 s[4:5], 1, v0
	s_andn2_b64 vcc, exec, s[30:31]
	s_cbranch_vccnz .LBB0_523
	ds_read_b128 v[176:179], v241 offset:16384
	ds_read_b128 v[192:195], v241 offset:17408
	ds_read_b128 v[172:175], v241 offset:18432
	ds_read_b128 v[188:191], v241 offset:19456
	ds_read_b128 v[168:171], v241 offset:20480
	ds_read_b128 v[184:187], v241 offset:21504
	ds_read_b128 v[164:167], v241 offset:22528
	ds_read_b128 v[180:183], v241 offset:23552
.LBB0_523:
	s_add_u32 s36, s34, 0xfffc0080
	s_addc_u32 s37, s35, -1
	s_cmp_eq_u32 s82, 12
	s_cselect_b32 s39, s1, s37
	s_cselect_b32 s38, s19, s36
	s_cselect_b32 s37, s17, s81
	s_cselect_b32 s36, s29, s80
	s_mov_b32 m0, s49
	v_lshl_add_u64 v[2:3], s[36:37], 0, v[198:199]
	s_add_u32 s88, s36, 0x40000
	global_load_lds_dwordx4 v[2:3], off
	v_lshl_add_u64 v[208:209], s[36:37], 0, v[202:203]
	s_mov_b32 m0, s54
	s_addc_u32 s89, s37, 0
	global_load_lds_dwordx4 v[208:209], off
	v_lshl_add_u64 v[210:211], s[88:89], 0, v[198:199]
	s_mov_b32 m0, s55
	v_lshl_add_u64 v[220:221], s[38:39], 0, v[200:201]
	global_load_lds_dwordx4 v[210:211], off
	v_lshl_add_u64 v[210:211], s[88:89], 0, v[202:203]
	s_mov_b32 m0, s56
	s_and_b64 vcc, exec, s[4:5]
	global_load_lds_dwordx4 v[210:211], off
	v_lshl_add_u64 v[210:211], s[38:39], 0, v[196:197]
	s_mov_b32 m0, s27
	s_nop 0
	global_load_lds_dwordx4 v[210:211], off
	s_mov_b32 m0, s57
	s_nop 0
	global_load_lds_dwordx4 v[220:221], off
	s_waitcnt vmcnt(8)
	s_waitcnt lgkmcnt(0)
	s_setprio 1
	s_barrier
	s_cbranch_vccnz .LBB0_525
; #define PG8_STAGE(bufoff, gbase, voff) do { _Pragma("unroll") for (int _i = 0; _i < 2; ++_i) \
;         __builtin_amdgcn_global_load_lds((const unsigned*)((const char*)(gbase) + (voff)[_i]), (PG8_LAS unsigned*)(lds + (bufoff) + ldsw + _i * 8192), 16, 0, 0); } while (0)
; #define PG8_LDA(dst, b, h) do { _Pragma("unroll") for (int m = 0; m < 4; ++m) _Pragma("unroll") for (int k = 0; k < 2; ++k) dst[m][k] = *(const PG8_LAS bf16x8*)(lds + PG8_SA(b, h) + aoff + m * 2048 + k * 1024); } while (0)
; #define PG8_LDB(dst, b, h) do { _Pragma("unroll") for (int n = 0; n < 2; ++n) _Pragma("unroll") for (int k = 0; k < 2; ++k) dst[n][k] = *(const PG8_LAS bf16x8*)(lds + PG8_SB(b, h) + boff + n * 2048 + k * 1024); } while (0)
; #define PG8_MMA(ai, bj, At, Bt) do { __builtin_amdgcn_s_setprio(1); _Pragma("unroll") for (int m = 0; m < 4; ++m) _Pragma("unroll") for (int n = 0; n < 2; ++n) _Pragma("unroll") for (int k = 0; k < 2; ++k) \
;         acc[ai][bj][m][n] = __builtin_amdgcn_mfma_f32_16x16x32_bf16(Bt[n][k], At[m][k], acc[ai][bj][m][n], 0, 0, 0); __builtin_amdgcn_s_setprio(0); } while (0)
; #define PG8_WAIT_V(n) asm volatile("s_waitcnt vmcnt(" #n ")" ::: "memory")
; #define PG8_WAIT_L(n) asm volatile("s_waitcnt lgkmcnt(" #n ")" ::: "memory")
; #define PG8_BAR __builtin_amdgcn_s_barrier()
; #define PG8_SCHED __builtin_amdgcn_sched_barrier(0)
; template <class Epi, class Sched, bool ALIGN_EPI = false, bool SP2 = false>
; __device__ __forceinline__ void gemm_phase(PG8_LAS unsigned char* lds, const Gemm g, const Sched& S, const Epi& E) {
;     ...
;             PG8_WAIT_V(8); PG8_WAIT_L(0); PG8_BAR; if (full) { PG8_MMA(1, 0, At, B0); PG8_MMA(1, 1, At, B1); } PG8_BAR; PG8_SCHED;
;             PG8_LDB(B0, 1, 0); PG8_LDB(B1, 1, 1); PG8_SCHED; PG8_LDA(At, 1, 0); PG8_STAGE(PG8_SA(0, 1), a2 + hstep, voffA);
;             PG8_WAIT_V(8); PG8_WAIT_L(0); PG8_BAR; PG8_MMA(0, 0, At, B0); PG8_MMA(0, 1, At, B1); PG8_BAR; PG8_SCHED;
;             if (full) PG8_LDA(At, 1, 1); PG8_STAGE(PG8_SB(1, 0), b3, voffB); PG8_STAGE(PG8_SB(1, 1), b3 + hstep, voffB); PG8_STAGE(PG8_SA(1, 0), a3, voffA);
	s_setprio 1
	s_waitcnt lgkmcnt(0)
	v_mfma_f32_16x16x32_bf16 v[64:67], v[148:151], v[176:179], v[64:67]
	v_mfma_f32_16x16x32_bf16 v[60:63], v[156:159], v[176:179], v[60:63]
	v_mfma_f32_16x16x32_bf16 v[48:51], v[148:151], v[172:175], v[48:51]
	v_mfma_f32_16x16x32_bf16 v[44:47], v[156:159], v[172:175], v[44:47]
	v_mfma_f32_16x16x32_bf16 v[32:35], v[148:151], v[168:171], v[32:35]
	v_mfma_f32_16x16x32_bf16 v[28:31], v[156:159], v[168:171], v[28:31]
	v_mfma_f32_16x16x32_bf16 v[16:19], v[148:151], v[164:167], v[16:19]
	v_mfma_f32_16x16x32_bf16 v[12:15], v[156:159], v[164:167], v[12:15]
	v_mfma_f32_16x16x32_bf16 v[64:67], v[152:155], v[192:195], v[64:67]
	v_mfma_f32_16x16x32_bf16 v[60:63], v[160:163], v[192:195], v[60:63]
	v_mfma_f32_16x16x32_bf16 v[48:51], v[152:155], v[188:191], v[48:51]
	v_mfma_f32_16x16x32_bf16 v[44:47], v[160:163], v[188:191], v[44:47]
	v_mfma_f32_16x16x32_bf16 v[32:35], v[152:155], v[184:187], v[32:35]
	v_mfma_f32_16x16x32_bf16 v[28:31], v[160:163], v[184:187], v[28:31]
	v_mfma_f32_16x16x32_bf16 v[16:19], v[152:155], v[180:183], v[16:19]
	v_mfma_f32_16x16x32_bf16 v[12:15], v[160:163], v[180:183], v[12:15]
	v_mfma_f32_16x16x32_bf16 v[56:59], v[132:135], v[176:179], v[56:59]
	v_mfma_f32_16x16x32_bf16 v[52:55], v[140:143], v[176:179], v[52:55]
	v_mfma_f32_16x16x32_bf16 v[40:43], v[132:135], v[172:175], v[40:43]
	v_mfma_f32_16x16x32_bf16 v[36:39], v[140:143], v[172:175], v[36:39]
	v_mfma_f32_16x16x32_bf16 v[24:27], v[132:135], v[168:171], v[24:27]
	v_mfma_f32_16x16x32_bf16 v[20:23], v[140:143], v[168:171], v[20:23]
	v_mfma_f32_16x16x32_bf16 v[8:11], v[132:135], v[164:167], v[8:11]
	v_mfma_f32_16x16x32_bf16 v[4:7], v[140:143], v[164:167], v[4:7]
	v_mfma_f32_16x16x32_bf16 v[56:59], v[136:139], v[192:195], v[56:59]
	v_mfma_f32_16x16x32_bf16 v[52:55], v[144:147], v[192:195], v[52:55]
	v_mfma_f32_16x16x32_bf16 v[40:43], v[136:139], v[188:191], v[40:43]
	v_mfma_f32_16x16x32_bf16 v[36:39], v[144:147], v[188:191], v[36:39]
	v_mfma_f32_16x16x32_bf16 v[24:27], v[136:139], v[184:187], v[24:27]
	v_mfma_f32_16x16x32_bf16 v[20:23], v[144:147], v[184:187], v[20:23]
	v_mfma_f32_16x16x32_bf16 v[8:11], v[136:139], v[180:183], v[8:11]
	v_mfma_f32_16x16x32_bf16 v[4:7], v[144:147], v[180:183], v[4:7]
.LBB0_525:
	s_barrier
	s_setprio 0
	v_add_u32_e32 v0, 0x18000, v225
	ds_read_b128 v[148:151], v0
	ds_read_b128 v[152:155], v0 offset:1024
	ds_read_b128 v[156:159], v0 offset:2048
	ds_read_b128 v[160:163], v0 offset:3072
	v_add_u32_e32 v0, 0x1c000, v225
	ds_read_b128 v[132:135], v0
	ds_read_b128 v[136:139], v0 offset:1024
	ds_read_b128 v[140:143], v0 offset:2048
	ds_read_b128 v[144:147], v0 offset:3072
	s_add_u32 s38, s38, 0x40000
	s_addc_u32 s39, s39, 0
	s_mov_b32 m0, s58
	v_lshl_add_u64 v[212:213], s[38:39], 0, v[196:197]
	ds_read_b128 v[176:179], v241 offset:32768
	ds_read_b128 v[192:195], v241 offset:33792
	ds_read_b128 v[172:175], v241 offset:34816
	ds_read_b128 v[188:191], v241 offset:35840
	ds_read_b128 v[168:171], v241 offset:36864
	ds_read_b128 v[184:187], v241 offset:37888
	ds_read_b128 v[164:167], v241 offset:38912
	ds_read_b128 v[180:183], v241 offset:39936
	global_load_lds_dwordx4 v[212:213], off
	v_lshl_add_u64 v[212:213], s[38:39], 0, v[200:201]
	s_mov_b32 m0, s59
	s_nop 0
	global_load_lds_dwordx4 v[212:213], off
	s_waitcnt vmcnt(8)
	s_waitcnt lgkmcnt(0)
	s_setprio 1
	s_barrier
	s_waitcnt lgkmcnt(0)
	v_mfma_f32_16x16x32_bf16 v[128:131], v[148:151], v[176:179], v[128:131]
	v_mfma_f32_16x16x32_bf16 v[124:127], v[156:159], v[176:179], v[124:127]
	v_mfma_f32_16x16x32_bf16 v[112:115], v[148:151], v[172:175], v[112:115]
	v_mfma_f32_16x16x32_bf16 v[108:111], v[156:159], v[172:175], v[108:111]
	v_mfma_f32_16x16x32_bf16 v[96:99], v[148:151], v[168:171], v[96:99]
	v_mfma_f32_16x16x32_bf16 v[92:95], v[156:159], v[168:171], v[92:95]
	v_mfma_f32_16x16x32_bf16 v[80:83], v[148:151], v[164:167], v[80:83]
	v_mfma_f32_16x16x32_bf16 v[76:79], v[156:159], v[164:167], v[76:79]
	v_mfma_f32_16x16x32_bf16 v[128:131], v[152:155], v[192:195], v[128:131]
	v_mfma_f32_16x16x32_bf16 v[124:127], v[160:163], v[192:195], v[124:127]
	v_mfma_f32_16x16x32_bf16 v[112:115], v[152:155], v[188:191], v[112:115]
	v_mfma_f32_16x16x32_bf16 v[108:111], v[160:163], v[188:191], v[108:111]
	v_mfma_f32_16x16x32_bf16 v[96:99], v[152:155], v[184:187], v[96:99]
	v_mfma_f32_16x16x32_bf16 v[92:95], v[160:163], v[184:187], v[92:95]
	v_mfma_f32_16x16x32_bf16 v[80:83], v[152:155], v[180:183], v[80:83]
	v_mfma_f32_16x16x32_bf16 v[76:79], v[160:163], v[180:183], v[76:79]
	v_mfma_f32_16x16x32_bf16 v[120:123], v[132:135], v[176:179], v[120:123]
	v_mfma_f32_16x16x32_bf16 v[116:119], v[140:143], v[176:179], v[116:119]
	v_mfma_f32_16x16x32_bf16 v[104:107], v[132:135], v[172:175], v[104:107]
	v_mfma_f32_16x16x32_bf16 v[100:103], v[140:143], v[172:175], v[100:103]
	v_mfma_f32_16x16x32_bf16 v[88:91], v[132:135], v[168:171], v[88:91]
	v_mfma_f32_16x16x32_bf16 v[84:87], v[140:143], v[168:171], v[84:87]
	v_mfma_f32_16x16x32_bf16 v[72:75], v[132:135], v[164:167], v[72:75]
	v_mfma_f32_16x16x32_bf16 v[68:71], v[140:143], v[164:167], v[68:71]
	v_mfma_f32_16x16x32_bf16 v[120:123], v[136:139], v[192:195], v[120:123]
	v_mfma_f32_16x16x32_bf16 v[116:119], v[144:147], v[192:195], v[116:119]
	v_mfma_f32_16x16x32_bf16 v[104:107], v[136:139], v[188:191], v[104:107]
	v_mfma_f32_16x16x32_bf16 v[100:103], v[144:147], v[188:191], v[100:103]
	v_mfma_f32_16x16x32_bf16 v[88:91], v[136:139], v[184:187], v[88:91]
	v_mfma_f32_16x16x32_bf16 v[84:87], v[144:147], v[184:187], v[84:87]
	v_mfma_f32_16x16x32_bf16 v[72:75], v[136:139], v[180:183], v[72:75]
	v_mfma_f32_16x16x32_bf16 v[68:71], v[144:147], v[180:183], v[68:71]
	s_barrier
	s_setprio 0
	s_and_b64 vcc, exec, s[4:5]
	s_cbranch_vccnz .LBB0_527
	ds_read_b128 v[176:179], v241 offset:49152
	ds_read_b128 v[192:195], v241 offset:50176
	ds_read_b128 v[172:175], v241 offset:51200
	ds_read_b128 v[188:191], v241 offset:52224
	ds_read_b128 v[168:171], v241 offset:53248
	ds_read_b128 v[184:187], v241 offset:54272
	ds_read_b128 v[164:167], v241 offset:55296
	ds_read_b128 v[180:183], v241 offset:56320
; #define PG8_STAGE(bufoff, gbase, voff) do { _Pragma("unroll") for (int _i = 0; _i < 2; ++_i) \
;         __builtin_amdgcn_global_load_lds((const unsigned*)((const char*)(gbase) + (voff)[_i]), (PG8_LAS unsigned*)(lds + (bufoff) + ldsw + _i * 8192), 16, 0, 0); } while (0)
; #define PG8_LDA(dst, b, h) do { _Pragma("unroll") for (int m = 0; m < 4; ++m) _Pragma("unroll") for (int k = 0; k < 2; ++k) dst[m][k] = *(const PG8_LAS bf16x8*)(lds + PG8_SA(b, h) + aoff + m * 2048 + k * 1024); } while (0)
; #define PG8_MMA(ai, bj, At, Bt) do { __builtin_amdgcn_s_setprio(1); _Pragma("unroll") for (int m = 0; m < 4; ++m) _Pragma("unroll") for (int n = 0; n < 2; ++n) _Pragma("unroll") for (int k = 0; k < 2; ++k) \
;         acc[ai][bj][m][n] = __builtin_amdgcn_mfma_f32_16x16x32_bf16(Bt[n][k], At[m][k], acc[ai][bj][m][n], 0, 0, 0); __builtin_amdgcn_s_setprio(0); } while (0)
; #define PG8_WAIT_V(n) asm volatile("s_waitcnt vmcnt(" #n ")" ::: "memory")
; #define PG8_WAIT_L(n) asm volatile("s_waitcnt lgkmcnt(" #n ")" ::: "memory")
; #define PG8_BAR __builtin_amdgcn_s_barrier()
; #define PG8_SCHED __builtin_amdgcn_sched_barrier(0)
; template <class Epi, class Sched, bool ALIGN_EPI = false, bool SP2 = false>
; __device__ __forceinline__ void gemm_phase(PG8_LAS unsigned char* lds, const Gemm g, const Sched& S, const Epi& E) {
;     ...
;             if (full) PG8_LDA(At, 1, 1); PG8_STAGE(PG8_SB(1, 0), b3, voffB); PG8_STAGE(PG8_SB(1, 1), b3 + hstep, voffB); PG8_STAGE(PG8_SA(1, 0), a3, voffA);
;             PG8_WAIT_V(8); PG8_WAIT_L(0); PG8_BAR; if (full) { PG8_MMA(1, 0, At, B0); PG8_MMA(1, 1, At, B1); } PG8_BAR; PG8_SCHED;
.LBB0_527:
	s_mov_b32 m0, s62
	v_lshl_add_u64 v[2:3], v[2:3], 0, s[52:53]
	s_add_u32 s36, s36, 0x40080
	global_load_lds_dwordx4 v[2:3], off
	v_lshl_add_u64 v[2:3], v[208:209], 0, s[52:53]
	s_mov_b32 m0, s63
	s_addc_u32 s37, s37, 0
	global_load_lds_dwordx4 v[2:3], off
	v_lshl_add_u64 v[2:3], s[36:37], 0, v[198:199]
	s_mov_b32 m0, s68
	s_and_b64 vcc, exec, s[4:5]
	global_load_lds_dwordx4 v[2:3], off
	v_lshl_add_u64 v[2:3], s[36:37], 0, v[202:203]
	s_mov_b32 m0, s69
	s_nop 0
	global_load_lds_dwordx4 v[2:3], off
	v_lshl_add_u64 v[2:3], v[210:211], 0, s[52:53]
	s_mov_b32 m0, s64
	s_nop 0
	global_load_lds_dwordx4 v[2:3], off
	v_lshl_add_u64 v[2:3], v[220:221], 0, s[52:53]
	s_mov_b32 m0, s65
	s_nop 0
	global_load_lds_dwordx4 v[2:3], off
	s_waitcnt vmcnt(8)
	s_waitcnt lgkmcnt(0)
	s_setprio 1
	s_barrier
	s_cbranch_vccnz .LBB0_520
	s_setprio 1
	s_waitcnt lgkmcnt(0)
	v_mfma_f32_16x16x32_bf16 v[64:67], v[148:151], v[176:179], v[64:67]
	v_mfma_f32_16x16x32_bf16 v[60:63], v[156:159], v[176:179], v[60:63]
	v_mfma_f32_16x16x32_bf16 v[48:51], v[148:151], v[172:175], v[48:51]
	v_mfma_f32_16x16x32_bf16 v[44:47], v[156:159], v[172:175], v[44:47]
	v_mfma_f32_16x16x32_bf16 v[32:35], v[148:151], v[168:171], v[32:35]
	v_mfma_f32_16x16x32_bf16 v[28:31], v[156:159], v[168:171], v[28:31]
	v_mfma_f32_16x16x32_bf16 v[16:19], v[148:151], v[164:167], v[16:19]
	v_mfma_f32_16x16x32_bf16 v[12:15], v[156:159], v[164:167], v[12:15]
	v_mfma_f32_16x16x32_bf16 v[64:67], v[152:155], v[192:195], v[64:67]
	v_mfma_f32_16x16x32_bf16 v[60:63], v[160:163], v[192:195], v[60:63]
	v_mfma_f32_16x16x32_bf16 v[48:51], v[152:155], v[188:191], v[48:51]
	v_mfma_f32_16x16x32_bf16 v[44:47], v[160:163], v[188:191], v[44:47]
	v_mfma_f32_16x16x32_bf16 v[32:35], v[152:155], v[184:187], v[32:35]
	v_mfma_f32_16x16x32_bf16 v[28:31], v[160:163], v[184:187], v[28:31]
	v_mfma_f32_16x16x32_bf16 v[16:19], v[152:155], v[180:183], v[16:19]
	v_mfma_f32_16x16x32_bf16 v[12:15], v[160:163], v[180:183], v[12:15]
	v_mfma_f32_16x16x32_bf16 v[56:59], v[132:135], v[176:179], v[56:59]
	v_mfma_f32_16x16x32_bf16 v[52:55], v[140:143], v[176:179], v[52:55]
	v_mfma_f32_16x16x32_bf16 v[40:43], v[132:135], v[172:175], v[40:43]
	v_mfma_f32_16x16x32_bf16 v[36:39], v[140:143], v[172:175], v[36:39]
	v_mfma_f32_16x16x32_bf16 v[24:27], v[132:135], v[168:171], v[24:27]
	v_mfma_f32_16x16x32_bf16 v[20:23], v[140:143], v[168:171], v[20:23]
	v_mfma_f32_16x16x32_bf16 v[8:11], v[132:135], v[164:167], v[8:11]
	v_mfma_f32_16x16x32_bf16 v[2:5], v[140:143], v[164:167], v[4:7]
	v_mfma_f32_16x16x32_bf16 v[56:59], v[136:139], v[192:195], v[56:59]
	v_mfma_f32_16x16x32_bf16 v[52:55], v[144:147], v[192:195], v[52:55]
	v_mfma_f32_16x16x32_bf16 v[40:43], v[136:139], v[188:191], v[40:43]
	v_mfma_f32_16x16x32_bf16 v[36:39], v[144:147], v[188:191], v[36:39]
	v_mfma_f32_16x16x32_bf16 v[24:27], v[136:139], v[184:187], v[24:27]
	v_mfma_f32_16x16x32_bf16 v[20:23], v[144:147], v[184:187], v[20:23]
	v_mfma_f32_16x16x32_bf16 v[8:11], v[136:139], v[180:183], v[8:11]
	v_mfma_f32_16x16x32_bf16 v[4:7], v[144:147], v[180:183], v[2:5]
	s_branch .LBB0_520

; #define PG8_STAGE(bufoff, gbase, voff) do { _Pragma("unroll") for (int _i = 0; _i < 2; ++_i) \
;         __builtin_amdgcn_global_load_lds((const unsigned*)((const char*)(gbase) + (voff)[_i]), (PG8_LAS unsigned*)(lds + (bufoff) + ldsw + _i * 8192), 16, 0, 0); } while (0)
; #define PG8_LDA(dst, b, h) do { _Pragma("unroll") for (int m = 0; m < 4; ++m) _Pragma("unroll") for (int k = 0; k < 2; ++k) dst[m][k] = *(const PG8_LAS bf16x8*)(lds + PG8_SA(b, h) + aoff + m * 2048 + k * 1024); } while (0)
; #define PG8_LDB(dst, b, h) do { _Pragma("unroll") for (int n = 0; n < 2; ++n) _Pragma("unroll") for (int k = 0; k < 2; ++k) dst[n][k] = *(const PG8_LAS bf16x8*)(lds + PG8_SB(b, h) + boff + n * 2048 + k * 1024); } while (0)
; #define PG8_MMA(ai, bj, At, Bt) do { __builtin_amdgcn_s_setprio(1); _Pragma("unroll") for (int m = 0; m < 4; ++m) _Pragma("unroll") for (int n = 0; n < 2; ++n) _Pragma("unroll") for (int k = 0; k < 2; ++k) \
;         acc[ai][bj][m][n] = __builtin_amdgcn_mfma_f32_16x16x32_bf16(Bt[n][k], At[m][k], acc[ai][bj][m][n], 0, 0, 0); __builtin_amdgcn_s_setprio(0); } while (0)
; #define PG8_WAIT_V(n) asm volatile("s_waitcnt vmcnt(" #n ")" ::: "memory")
; #define PG8_WAIT_L(n) asm volatile("s_waitcnt lgkmcnt(" #n ")" ::: "memory")
; #define PG8_BAR __builtin_amdgcn_s_barrier()
; #define PG8_SCHED __builtin_amdgcn_sched_barrier(0)
; template <class Epi, class Sched, bool ALIGN_EPI = false, bool SP2 = false>
; __device__ __forceinline__ void gemm_phase(PG8_LAS unsigned char* lds, const Gemm g, const Sched& S, const Epi& E) {
;     ...
;             const bool last = (t == nt - 2);
;             const char* a1 = cA + (size_t)(t + 1) * kstep;
;             const char* a2 = last ? nA : cA + (size_t)(t + 2) * kstep; const char* b2 = last ? nB : cB + (size_t)(t + 2) * kstep;
;             const char* a3 = a2 + kstep; const char* b3 = b2 + kstep;
;             if (last && has_next) S.a_ready(nxt);
;             if constexpr (SP2) {
;             PG8_LDB(B0, 0, 0); PG8_LDB(B1, 0, 1); PG8_SCHED; PG8_LDA(At, 0, 0); PG8_STAGE(PG8_SA(1, 1), a1 + hstep, voffA);
;             PG8_WAIT_V(8); PG8_WAIT_L(0); PG8_BAR; PG8_MMA(0, 0, At, B0); PG8_MMA(0, 1, At, B1); PG8_BAR; PG8_SCHED;
;             if (full) PG8_LDA(At, 0, 1); PG8_STAGE(PG8_SB(0, 0), b2, voffB); PG8_STAGE(PG8_SB(0, 1), b2 + hstep, voffB); PG8_STAGE(PG8_SA(0, 0), a2, voffA);
.LBB0_1038:
	s_add_u32 s27, s6, 0xfffe0080
	s_addc_u32 s28, s7, -1
	s_add_i32 s54, 0, 0x10000
	s_cmp_eq_u32 s25, 4
	s_cselect_b32 s31, s21, s28
	s_cselect_b32 s30, s20, s27
	v_add_u32_e32 v0, s54, v179
	s_cselect_b32 s29, s0, s19
	s_cselect_b32 s28, s1, s17
	s_add_i32 s27, 0, 0x14000
	ds_read_b128 v[144:147], v0
	ds_read_b128 v[148:151], v0 offset:1024
	ds_read_b128 v[152:155], v0 offset:2048
	ds_read_b128 v[156:159], v0 offset:3072
	v_add_u32_e32 v0, s27, v179
	ds_read_b128 v[160:163], v0
	ds_read_b128 v[164:167], v0 offset:1024
	ds_read_b128 v[168:171], v0 offset:2048
	ds_read_b128 v[172:175], v0 offset:3072
	v_lshl_add_u64 v[2:3], s[6:7], 0, v[140:141]
	s_add_i32 m0, s39, 0xc000
	ds_read_b128 v[182:185], v181
	ds_read_b128 v[186:189], v181 offset:1024
	ds_read_b128 v[190:193], v181 offset:2048
	ds_read_b128 v[194:197], v181 offset:3072
	ds_read_b128 v[198:201], v181 offset:4096
	ds_read_b128 v[202:205], v181 offset:5120
	ds_read_b128 v[206:209], v181 offset:6144
	ds_read_b128 v[220:223], v181 offset:7168
	global_load_lds_dwordx4 v[2:3], off
	v_lshl_add_u64 v[2:3], s[6:7], 0, v[142:143]
	s_add_i32 m0, s39, 0xe000
	s_nop 0
	global_load_lds_dwordx4 v[2:3], off
	s_waitcnt vmcnt(8)
	s_waitcnt lgkmcnt(0)
	s_setprio 1
	s_barrier
	s_waitcnt lgkmcnt(0)
	v_mfma_f32_16x16x32_bf16 v[128:131], v[144:147], v[182:185], v[128:131]
	v_mfma_f32_16x16x32_bf16 v[124:127], v[152:155], v[182:185], v[124:127]
	v_mfma_f32_16x16x32_bf16 v[120:123], v[144:147], v[190:193], v[120:123]
	v_mfma_f32_16x16x32_bf16 v[116:119], v[152:155], v[190:193], v[116:119]
	v_mfma_f32_16x16x32_bf16 v[112:115], v[144:147], v[198:201], v[112:115]
	v_mfma_f32_16x16x32_bf16 v[108:111], v[152:155], v[198:201], v[108:111]
	v_mfma_f32_16x16x32_bf16 v[104:107], v[144:147], v[206:209], v[104:107]
	v_mfma_f32_16x16x32_bf16 v[100:103], v[152:155], v[206:209], v[100:103]
	v_mfma_f32_16x16x32_bf16 v[128:131], v[148:151], v[186:189], v[128:131]
	v_mfma_f32_16x16x32_bf16 v[124:127], v[156:159], v[186:189], v[124:127]
	v_mfma_f32_16x16x32_bf16 v[120:123], v[148:151], v[194:197], v[120:123]
	v_mfma_f32_16x16x32_bf16 v[116:119], v[156:159], v[194:197], v[116:119]
	v_mfma_f32_16x16x32_bf16 v[112:115], v[148:151], v[202:205], v[112:115]
	v_mfma_f32_16x16x32_bf16 v[108:111], v[156:159], v[202:205], v[108:111]
	v_mfma_f32_16x16x32_bf16 v[104:107], v[148:151], v[220:223], v[104:107]
	v_mfma_f32_16x16x32_bf16 v[100:103], v[156:159], v[220:223], v[100:103]
	v_mfma_f32_16x16x32_bf16 v[96:99], v[160:163], v[182:185], v[96:99]
	v_mfma_f32_16x16x32_bf16 v[92:95], v[168:171], v[182:185], v[92:95]
	v_mfma_f32_16x16x32_bf16 v[88:91], v[160:163], v[190:193], v[88:91]
	v_mfma_f32_16x16x32_bf16 v[84:87], v[168:171], v[190:193], v[84:87]
	v_mfma_f32_16x16x32_bf16 v[80:83], v[160:163], v[198:201], v[80:83]
	v_mfma_f32_16x16x32_bf16 v[76:79], v[168:171], v[198:201], v[76:79]
	v_mfma_f32_16x16x32_bf16 v[72:75], v[160:163], v[206:209], v[72:75]
	v_mfma_f32_16x16x32_bf16 v[68:71], v[168:171], v[206:209], v[68:71]
	v_mfma_f32_16x16x32_bf16 v[96:99], v[164:167], v[186:189], v[96:99]
	v_mfma_f32_16x16x32_bf16 v[92:95], v[172:175], v[186:189], v[92:95]
	v_mfma_f32_16x16x32_bf16 v[88:91], v[164:167], v[194:197], v[88:91]
	v_mfma_f32_16x16x32_bf16 v[84:87], v[172:175], v[194:197], v[84:87]
	v_mfma_f32_16x16x32_bf16 v[80:83], v[164:167], v[202:205], v[80:83]
	v_mfma_f32_16x16x32_bf16 v[76:79], v[172:175], v[202:205], v[76:79]
	v_mfma_f32_16x16x32_bf16 v[72:75], v[164:167], v[220:223], v[72:75]
	v_mfma_f32_16x16x32_bf16 v[68:71], v[172:175], v[220:223], v[68:71]
	s_barrier
	s_setprio 0
	s_add_i32 s54, s54, s38
	v_lshl_add_u64 v[176:177], s[28:29], 0, v[134:135]
	s_mov_b32 m0, s54
	ds_read_b128 v[182:185], v181 offset:16384
	ds_read_b128 v[186:189], v181 offset:17408
	ds_read_b128 v[190:193], v181 offset:18432
	ds_read_b128 v[194:197], v181 offset:19456
	ds_read_b128 v[198:201], v181 offset:20480
	ds_read_b128 v[202:205], v181 offset:21504
	ds_read_b128 v[206:209], v181 offset:22528
	ds_read_b128 v[220:223], v181 offset:23552
	global_load_lds_dwordx4 v[176:177], off
	s_add_i32 m0, s54, 0x2000
	s_add_u32 s54, s28, 0x20000
	v_lshl_add_u64 v[210:211], s[28:29], 0, v[138:139]
	s_addc_u32 s55, s29, 0
	s_add_i32 s27, s27, s38
	global_load_lds_dwordx4 v[210:211], off
	v_lshl_add_u64 v[2:3], s[54:55], 0, v[134:135]
	s_mov_b32 m0, s27
	v_lshl_add_u64 v[212:213], s[30:31], 0, v[132:133]
	global_load_lds_dwordx4 v[2:3], off
	v_lshl_add_u64 v[2:3], s[54:55], 0, v[138:139]
	s_add_i32 m0, s27, 0x2000
	v_lshl_add_u64 v[214:215], s[30:31], 0, v[136:137]
	global_load_lds_dwordx4 v[2:3], off
	s_mov_b32 m0, s39
	s_nop 0
	global_load_lds_dwordx4 v[212:213], off
	s_mov_b32 m0, s40
	s_nop 0
	global_load_lds_dwordx4 v[214:215], off
	s_waitcnt vmcnt(8)
	s_waitcnt lgkmcnt(0)
	s_setprio 1
	s_barrier
; #define PG8_STAGE(bufoff, gbase, voff) do { _Pragma("unroll") for (int _i = 0; _i < 2; ++_i) \
;         __builtin_amdgcn_global_load_lds((const unsigned*)((const char*)(gbase) + (voff)[_i]), (PG8_LAS unsigned*)(lds + (bufoff) + ldsw + _i * 8192), 16, 0, 0); } while (0)
; #define PG8_LDA(dst, b, h) do { _Pragma("unroll") for (int m = 0; m < 4; ++m) _Pragma("unroll") for (int k = 0; k < 2; ++k) dst[m][k] = *(const PG8_LAS bf16x8*)(lds + PG8_SA(b, h) + aoff + m * 2048 + k * 1024); } while (0)
; #define PG8_LDB(dst, b, h) do { _Pragma("unroll") for (int n = 0; n < 2; ++n) _Pragma("unroll") for (int k = 0; k < 2; ++k) dst[n][k] = *(const PG8_LAS bf16x8*)(lds + PG8_SB(b, h) + boff + n * 2048 + k * 1024); } while (0)
; #define PG8_MMA(ai, bj, At, Bt) do { __builtin_amdgcn_s_setprio(1); _Pragma("unroll") for (int m = 0; m < 4; ++m) _Pragma("unroll") for (int n = 0; n < 2; ++n) _Pragma("unroll") for (int k = 0; k < 2; ++k) \
;         acc[ai][bj][m][n] = __builtin_amdgcn_mfma_f32_16x16x32_bf16(Bt[n][k], At[m][k], acc[ai][bj][m][n], 0, 0, 0); __builtin_amdgcn_s_setprio(0); } while (0)
; #define PG8_WAIT_V(n) asm volatile("s_waitcnt vmcnt(" #n ")" ::: "memory")
; #define PG8_WAIT_L(n) asm volatile("s_waitcnt lgkmcnt(" #n ")" ::: "memory")
; #define PG8_BAR __builtin_amdgcn_s_barrier()
; #define PG8_SCHED __builtin_amdgcn_sched_barrier(0)
; template <class Epi, class Sched, bool ALIGN_EPI = false, bool SP2 = false>
; __device__ __forceinline__ void gemm_phase(PG8_LAS unsigned char* lds, const Gemm g, const Sched& S, const Epi& E) {
;     ...
;             PG8_WAIT_V(8); PG8_WAIT_L(0); PG8_BAR; if (full) { PG8_MMA(1, 0, At, B0); PG8_MMA(1, 1, At, B1); } PG8_BAR; PG8_SCHED;
;             PG8_LDB(B0, 1, 0); PG8_LDB(B1, 1, 1); PG8_SCHED; PG8_LDA(At, 1, 0); PG8_STAGE(PG8_SA(0, 1), a2 + hstep, voffA);
;             PG8_WAIT_V(8); PG8_WAIT_L(0); PG8_BAR; PG8_MMA(0, 0, At, B0); PG8_MMA(0, 1, At, B1); PG8_BAR; PG8_SCHED;
	s_waitcnt lgkmcnt(0)
	v_mfma_f32_16x16x32_bf16 v[64:67], v[144:147], v[182:185], v[64:67]
	v_mfma_f32_16x16x32_bf16 v[60:63], v[152:155], v[182:185], v[60:63]
	v_mfma_f32_16x16x32_bf16 v[56:59], v[144:147], v[190:193], v[56:59]
	v_mfma_f32_16x16x32_bf16 v[52:55], v[152:155], v[190:193], v[52:55]
	v_mfma_f32_16x16x32_bf16 v[48:51], v[144:147], v[198:201], v[48:51]
	v_mfma_f32_16x16x32_bf16 v[44:47], v[152:155], v[198:201], v[44:47]
	v_mfma_f32_16x16x32_bf16 v[40:43], v[144:147], v[206:209], v[40:43]
	v_mfma_f32_16x16x32_bf16 v[36:39], v[152:155], v[206:209], v[36:39]
	v_mfma_f32_16x16x32_bf16 v[64:67], v[148:151], v[186:189], v[64:67]
	v_mfma_f32_16x16x32_bf16 v[60:63], v[156:159], v[186:189], v[60:63]
	v_mfma_f32_16x16x32_bf16 v[56:59], v[148:151], v[194:197], v[56:59]
	v_mfma_f32_16x16x32_bf16 v[52:55], v[156:159], v[194:197], v[52:55]
	v_mfma_f32_16x16x32_bf16 v[48:51], v[148:151], v[202:205], v[48:51]
	v_mfma_f32_16x16x32_bf16 v[44:47], v[156:159], v[202:205], v[44:47]
	v_mfma_f32_16x16x32_bf16 v[40:43], v[148:151], v[220:223], v[40:43]
	v_mfma_f32_16x16x32_bf16 v[36:39], v[156:159], v[220:223], v[36:39]
	v_mfma_f32_16x16x32_bf16 v[32:35], v[160:163], v[182:185], v[32:35]
	v_mfma_f32_16x16x32_bf16 v[28:31], v[168:171], v[182:185], v[28:31]
	v_mfma_f32_16x16x32_bf16 v[24:27], v[160:163], v[190:193], v[24:27]
	v_mfma_f32_16x16x32_bf16 v[20:23], v[168:171], v[190:193], v[20:23]
	v_mfma_f32_16x16x32_bf16 v[16:19], v[160:163], v[198:201], v[16:19]
	v_mfma_f32_16x16x32_bf16 v[12:15], v[168:171], v[198:201], v[12:15]
	v_mfma_f32_16x16x32_bf16 v[8:11], v[160:163], v[206:209], v[8:11]
	v_mfma_f32_16x16x32_bf16 v[2:5], v[168:171], v[206:209], v[4:7]
	v_mfma_f32_16x16x32_bf16 v[32:35], v[164:167], v[186:189], v[32:35]
	v_mfma_f32_16x16x32_bf16 v[28:31], v[172:175], v[186:189], v[28:31]
	v_mfma_f32_16x16x32_bf16 v[24:27], v[164:167], v[194:197], v[24:27]
	v_mfma_f32_16x16x32_bf16 v[20:23], v[172:175], v[194:197], v[20:23]
	v_mfma_f32_16x16x32_bf16 v[16:19], v[164:167], v[202:205], v[16:19]
	v_mfma_f32_16x16x32_bf16 v[12:15], v[172:175], v[202:205], v[12:15]
	v_mfma_f32_16x16x32_bf16 v[8:11], v[164:167], v[220:223], v[8:11]
	v_mfma_f32_16x16x32_bf16 v[2:5], v[172:175], v[220:223], v[2:5]
	s_barrier
	s_setprio 0
	s_add_i32 s27, 0, 0x18000
	v_add_u32_e32 v0, s27, v179
	s_add_i32 s54, 0, 0x1c000
	ds_read_b128 v[144:147], v0
	ds_read_b128 v[148:151], v0 offset:1024
	ds_read_b128 v[152:155], v0 offset:2048
	ds_read_b128 v[156:159], v0 offset:3072
	v_add_u32_e32 v0, s54, v179
	ds_read_b128 v[160:163], v0
	ds_read_b128 v[164:167], v0 offset:1024
	ds_read_b128 v[168:171], v0 offset:2048
	ds_read_b128 v[172:175], v0 offset:3072
	s_add_u32 s30, s30, 0x20000
	s_addc_u32 s31, s31, 0
	s_mov_b32 m0, s41
	v_lshl_add_u64 v[6:7], s[30:31], 0, v[132:133]
	ds_read_b128 v[182:185], v181 offset:32768
	ds_read_b128 v[186:189], v181 offset:33792
	ds_read_b128 v[190:193], v181 offset:34816
	ds_read_b128 v[194:197], v181 offset:35840
	ds_read_b128 v[198:201], v181 offset:36864
	ds_read_b128 v[202:205], v181 offset:37888
	ds_read_b128 v[206:209], v181 offset:38912
	ds_read_b128 v[220:223], v181 offset:39936
	global_load_lds_dwordx4 v[6:7], off
	v_lshl_add_u64 v[6:7], s[30:31], 0, v[136:137]
	s_mov_b32 m0, s42
	s_nop 0
	global_load_lds_dwordx4 v[6:7], off
	s_waitcnt vmcnt(8)
	s_waitcnt lgkmcnt(0)
	s_setprio 1
	s_barrier
	s_waitcnt lgkmcnt(0)
	v_mfma_f32_16x16x32_bf16 v[128:131], v[144:147], v[182:185], v[128:131]
	v_mfma_f32_16x16x32_bf16 v[124:127], v[152:155], v[182:185], v[124:127]
	v_mfma_f32_16x16x32_bf16 v[120:123], v[144:147], v[190:193], v[120:123]
	v_mfma_f32_16x16x32_bf16 v[116:119], v[152:155], v[190:193], v[116:119]
	v_mfma_f32_16x16x32_bf16 v[112:115], v[144:147], v[198:201], v[112:115]
	v_mfma_f32_16x16x32_bf16 v[108:111], v[152:155], v[198:201], v[108:111]
	v_mfma_f32_16x16x32_bf16 v[104:107], v[144:147], v[206:209], v[104:107]
	v_mfma_f32_16x16x32_bf16 v[100:103], v[152:155], v[206:209], v[100:103]
	v_mfma_f32_16x16x32_bf16 v[128:131], v[148:151], v[186:189], v[128:131]
	v_mfma_f32_16x16x32_bf16 v[124:127], v[156:159], v[186:189], v[124:127]
	v_mfma_f32_16x16x32_bf16 v[120:123], v[148:151], v[194:197], v[120:123]
	v_mfma_f32_16x16x32_bf16 v[116:119], v[156:159], v[194:197], v[116:119]
	v_mfma_f32_16x16x32_bf16 v[112:115], v[148:151], v[202:205], v[112:115]
	v_mfma_f32_16x16x32_bf16 v[108:111], v[156:159], v[202:205], v[108:111]
	v_mfma_f32_16x16x32_bf16 v[104:107], v[148:151], v[220:223], v[104:107]
	v_mfma_f32_16x16x32_bf16 v[100:103], v[156:159], v[220:223], v[100:103]
	v_mfma_f32_16x16x32_bf16 v[96:99], v[160:163], v[182:185], v[96:99]
	v_mfma_f32_16x16x32_bf16 v[92:95], v[168:171], v[182:185], v[92:95]
	v_mfma_f32_16x16x32_bf16 v[88:91], v[160:163], v[190:193], v[88:91]
	v_mfma_f32_16x16x32_bf16 v[84:87], v[168:171], v[190:193], v[84:87]
	v_mfma_f32_16x16x32_bf16 v[80:83], v[160:163], v[198:201], v[80:83]
	v_mfma_f32_16x16x32_bf16 v[76:79], v[168:171], v[198:201], v[76:79]
	v_mfma_f32_16x16x32_bf16 v[72:75], v[160:163], v[206:209], v[72:75]
	v_mfma_f32_16x16x32_bf16 v[68:71], v[168:171], v[206:209], v[68:71]
	v_mfma_f32_16x16x32_bf16 v[96:99], v[164:167], v[186:189], v[96:99]
	v_mfma_f32_16x16x32_bf16 v[92:95], v[172:175], v[186:189], v[92:95]
	v_mfma_f32_16x16x32_bf16 v[88:91], v[164:167], v[194:197], v[88:91]
	v_mfma_f32_16x16x32_bf16 v[84:87], v[172:175], v[194:197], v[84:87]
	v_mfma_f32_16x16x32_bf16 v[80:83], v[164:167], v[202:205], v[80:83]
	v_mfma_f32_16x16x32_bf16 v[76:79], v[172:175], v[202:205], v[76:79]
	v_mfma_f32_16x16x32_bf16 v[72:75], v[164:167], v[220:223], v[72:75]
	v_mfma_f32_16x16x32_bf16 v[68:71], v[172:175], v[220:223], v[68:71]
	s_barrier
; #define PG8_STAGE(bufoff, gbase, voff) do { _Pragma("unroll") for (int _i = 0; _i < 2; ++_i) \
;         __builtin_amdgcn_global_load_lds((const unsigned*)((const char*)(gbase) + (voff)[_i]), (PG8_LAS unsigned*)(lds + (bufoff) + ldsw + _i * 8192), 16, 0, 0); } while (0)
; #define PG8_LDA(dst, b, h) do { _Pragma("unroll") for (int m = 0; m < 4; ++m) _Pragma("unroll") for (int k = 0; k < 2; ++k) dst[m][k] = *(const PG8_LAS bf16x8*)(lds + PG8_SA(b, h) + aoff + m * 2048 + k * 1024); } while (0)
; #define PG8_MMA(ai, bj, At, Bt) do { __builtin_amdgcn_s_setprio(1); _Pragma("unroll") for (int m = 0; m < 4; ++m) _Pragma("unroll") for (int n = 0; n < 2; ++n) _Pragma("unroll") for (int k = 0; k < 2; ++k) \
;         acc[ai][bj][m][n] = __builtin_amdgcn_mfma_f32_16x16x32_bf16(Bt[n][k], At[m][k], acc[ai][bj][m][n], 0, 0, 0); __builtin_amdgcn_s_setprio(0); } while (0)
; #define PG8_WAIT_V(n) asm volatile("s_waitcnt vmcnt(" #n ")" ::: "memory")
; #define PG8_WAIT_L(n) asm volatile("s_waitcnt lgkmcnt(" #n ")" ::: "memory")
; #define PG8_BAR __builtin_amdgcn_s_barrier()
; #define PG8_SCHED __builtin_amdgcn_sched_barrier(0)
; template <class Epi, class Sched, bool ALIGN_EPI = false, bool SP2 = false>
; __device__ __forceinline__ void gemm_phase(PG8_LAS unsigned char* lds, const Gemm g, const Sched& S, const Epi& E) {
;     ...
;             if (full) PG8_LDA(At, 1, 1); PG8_STAGE(PG8_SB(1, 0), b3, voffB); PG8_STAGE(PG8_SB(1, 1), b3 + hstep, voffB); PG8_STAGE(PG8_SA(1, 0), a3, voffA);
;             PG8_WAIT_V(8); PG8_WAIT_L(0); PG8_BAR; if (full) { PG8_MMA(1, 0, At, B0); PG8_MMA(1, 1, At, B1); } PG8_BAR; PG8_SCHED;
;     ...
;         if constexpr (ALIGN_EPI) { if (wr == 0) PG8_BAR; }
	s_setprio 0
	s_add_i32 s27, s27, s38
	v_lshl_add_u64 v[6:7], v[176:177], 0, s[52:53]
	s_mov_b32 m0, s27
	ds_read_b128 v[182:185], v181 offset:49152
	ds_read_b128 v[186:189], v181 offset:50176
	ds_read_b128 v[190:193], v181 offset:51200
	ds_read_b128 v[194:197], v181 offset:52224
	ds_read_b128 v[198:201], v181 offset:53248
	ds_read_b128 v[202:205], v181 offset:54272
	ds_read_b128 v[206:209], v181 offset:55296
	ds_read_b128 v[220:223], v181 offset:56320
	global_load_lds_dwordx4 v[6:7], off
	s_add_i32 m0, s27, 0x2000
	s_add_u32 s28, s28, 0x20080
	v_lshl_add_u64 v[6:7], v[210:211], 0, s[52:53]
	s_addc_u32 s29, s29, 0
	s_add_i32 s27, s54, s38
	global_load_lds_dwordx4 v[6:7], off
	v_lshl_add_u64 v[6:7], s[28:29], 0, v[134:135]
	s_mov_b32 m0, s27
	s_nop 0
	global_load_lds_dwordx4 v[6:7], off
	v_lshl_add_u64 v[6:7], s[28:29], 0, v[138:139]
	s_add_i32 m0, s27, 0x2000
	s_nop 0
	global_load_lds_dwordx4 v[6:7], off
	v_lshl_add_u64 v[6:7], v[212:213], 0, s[52:53]
	s_mov_b32 m0, s43
	s_nop 0
	global_load_lds_dwordx4 v[6:7], off
	v_lshl_add_u64 v[6:7], v[214:215], 0, s[52:53]
	s_mov_b32 m0, s44
	s_nop 0
	global_load_lds_dwordx4 v[6:7], off
	s_waitcnt vmcnt(8)
	s_waitcnt lgkmcnt(0)
	s_setprio 1
	s_barrier
	s_waitcnt lgkmcnt(0)
	v_mfma_f32_16x16x32_bf16 v[64:67], v[144:147], v[182:185], v[64:67]
	v_mfma_f32_16x16x32_bf16 v[60:63], v[152:155], v[182:185], v[60:63]
	v_mfma_f32_16x16x32_bf16 v[56:59], v[144:147], v[190:193], v[56:59]
	v_mfma_f32_16x16x32_bf16 v[52:55], v[152:155], v[190:193], v[52:55]
	v_mfma_f32_16x16x32_bf16 v[48:51], v[144:147], v[198:201], v[48:51]
	v_mfma_f32_16x16x32_bf16 v[44:47], v[152:155], v[198:201], v[44:47]
	v_mfma_f32_16x16x32_bf16 v[40:43], v[144:147], v[206:209], v[40:43]
	v_mfma_f32_16x16x32_bf16 v[36:39], v[152:155], v[206:209], v[36:39]
	v_mfma_f32_16x16x32_bf16 v[64:67], v[148:151], v[186:189], v[64:67]
	v_mfma_f32_16x16x32_bf16 v[60:63], v[156:159], v[186:189], v[60:63]
	v_mfma_f32_16x16x32_bf16 v[56:59], v[148:151], v[194:197], v[56:59]
	v_mfma_f32_16x16x32_bf16 v[52:55], v[156:159], v[194:197], v[52:55]
	v_mfma_f32_16x16x32_bf16 v[48:51], v[148:151], v[202:205], v[48:51]
	v_mfma_f32_16x16x32_bf16 v[44:47], v[156:159], v[202:205], v[44:47]
	v_mfma_f32_16x16x32_bf16 v[40:43], v[148:151], v[220:223], v[40:43]
	v_mfma_f32_16x16x32_bf16 v[36:39], v[156:159], v[220:223], v[36:39]
	v_mfma_f32_16x16x32_bf16 v[32:35], v[160:163], v[182:185], v[32:35]
	v_mfma_f32_16x16x32_bf16 v[28:31], v[168:171], v[182:185], v[28:31]
	v_mfma_f32_16x16x32_bf16 v[24:27], v[160:163], v[190:193], v[24:27]
	v_mfma_f32_16x16x32_bf16 v[20:23], v[168:171], v[190:193], v[20:23]
	v_mfma_f32_16x16x32_bf16 v[16:19], v[160:163], v[198:201], v[16:19]
	v_mfma_f32_16x16x32_bf16 v[12:15], v[168:171], v[198:201], v[12:15]
	v_mfma_f32_16x16x32_bf16 v[6:9], v[160:163], v[206:209], v[8:11]
	v_mfma_f32_16x16x32_bf16 v[2:5], v[168:171], v[206:209], v[2:5]
	v_mfma_f32_16x16x32_bf16 v[32:35], v[164:167], v[186:189], v[32:35]
	v_mfma_f32_16x16x32_bf16 v[28:31], v[172:175], v[186:189], v[28:31]
	v_mfma_f32_16x16x32_bf16 v[24:27], v[164:167], v[194:197], v[24:27]
	v_mfma_f32_16x16x32_bf16 v[20:23], v[172:175], v[194:197], v[20:23]
	v_mfma_f32_16x16x32_bf16 v[16:19], v[164:167], v[202:205], v[16:19]
	v_mfma_f32_16x16x32_bf16 v[12:15], v[172:175], v[202:205], v[12:15]
	v_mfma_f32_16x16x32_bf16 v[8:11], v[164:167], v[220:223], v[6:9]
	v_mfma_f32_16x16x32_bf16 v[4:7], v[172:175], v[220:223], v[2:5]
	s_barrier
	s_setprio 0
	s_add_i32 s25, s25, 2
	s_add_u32 s6, s6, 0x100
	s_addc_u32 s7, s7, 0
	s_add_u32 s17, s17, 0x100
	s_addc_u32 s19, s19, 0
	s_cmp_gt_u32 s25, 5
	s_cbranch_scc0 .LBB0_1038
	s_and_b64 vcc, exec, s[14:15]
	s_cbranch_vccz .LBB0_1041
	s_barrier

; #define PG8_STAGE(bufoff, gbase, voff) do { _Pragma("unroll") for (int _i = 0; _i < 2; ++_i) \
;         __builtin_amdgcn_global_load_lds((const unsigned*)((const char*)(gbase) + (voff)[_i]), (PG8_LAS unsigned*)(lds + (bufoff) + ldsw + _i * 8192), 16, 0, 0); } while (0)
; #define PG8_LDA(dst, b, h) do { _Pragma("unroll") for (int m = 0; m < 4; ++m) _Pragma("unroll") for (int k = 0; k < 2; ++k) dst[m][k] = *(const PG8_LAS bf16x8*)(lds + PG8_SA(b, h) + aoff + m * 2048 + k * 1024); } while (0)
; #define PG8_LDB(dst, b, h) do { _Pragma("unroll") for (int n = 0; n < 2; ++n) _Pragma("unroll") for (int k = 0; k < 2; ++k) dst[n][k] = *(const PG8_LAS bf16x8*)(lds + PG8_SB(b, h) + boff + n * 2048 + k * 1024); } while (0)
; #define PG8_MMA(ai, bj, At, Bt) do { __builtin_amdgcn_s_setprio(1); _Pragma("unroll") for (int m = 0; m < 4; ++m) _Pragma("unroll") for (int n = 0; n < 2; ++n) _Pragma("unroll") for (int k = 0; k < 2; ++k) \
;         acc[ai][bj][m][n] = __builtin_amdgcn_mfma_f32_16x16x32_bf16(Bt[n][k], At[m][k], acc[ai][bj][m][n], 0, 0, 0); __builtin_amdgcn_s_setprio(0); } while (0)
; #define PG8_WAIT_V(n) asm volatile("s_waitcnt vmcnt(" #n ")" ::: "memory")
; #define PG8_WAIT_L(n) asm volatile("s_waitcnt lgkmcnt(" #n ")" ::: "memory")
; #define PG8_BAR __builtin_amdgcn_s_barrier()
; #define PG8_SCHED __builtin_amdgcn_sched_barrier(0)
; template <class Epi, class Sched, bool ALIGN_EPI = false, bool SP2 = false>
; __device__ __forceinline__ void gemm_phase(PG8_LAS unsigned char* lds, const Gemm g, const Sched& S, const Epi& E) {
;     ...
;             const bool last = (t == nt - 2);
;             const char* a1 = cA + (size_t)(t + 1) * kstep;
;             const char* a2 = last ? nA : cA + (size_t)(t + 2) * kstep; const char* b2 = last ? nB : cB + (size_t)(t + 2) * kstep;
;             const char* a3 = a2 + kstep; const char* b3 = b2 + kstep;
;             if (last && has_next) S.a_ready(nxt);
;             if constexpr (SP2) {
;             PG8_LDB(B0, 0, 0); PG8_LDB(B1, 0, 1); PG8_SCHED; PG8_LDA(At, 0, 0); PG8_STAGE(PG8_SA(1, 1), a1 + hstep, voffA);
;             PG8_WAIT_V(8); PG8_WAIT_L(0); PG8_BAR; PG8_MMA(0, 0, At, B0); PG8_MMA(0, 1, At, B1); PG8_BAR; PG8_SCHED;
;             if (full) PG8_LDA(At, 0, 1); PG8_STAGE(PG8_SB(0, 0), b2, voffB); PG8_STAGE(PG8_SB(0, 1), b2 + hstep, voffB); PG8_STAGE(PG8_SA(0, 0), a2, voffA);
.LBB0_1149:
	s_add_u32 s30, s18, s28
	s_addc_u32 s31, s19, s29
	s_add_u32 s30, s30, 0x100
	s_addc_u32 s31, s31, 0
	s_add_u32 s62, s57, s28
	s_addc_u32 s63, s58, s29
	s_add_i32 s64, 0, 0x10000
	s_cmpk_eq_i32 s28, 0x700
	s_cselect_b32 s35, s23, s31
	s_cselect_b32 s34, s59, s30
	v_add_u32_e32 v143, s64, v140
	s_cselect_b32 s31, s21, s63
	s_cselect_b32 s30, s60, s62
	s_add_i32 s65, 0, 0x14000
	ds_read_b128 v[144:147], v143
	ds_read_b128 v[148:151], v143 offset:1024
	ds_read_b128 v[152:155], v143 offset:2048
	ds_read_b128 v[156:159], v143 offset:3072
	v_add_u32_e32 v143, s65, v140
	ds_read_b128 v[160:163], v143
	ds_read_b128 v[164:167], v143 offset:1024
	ds_read_b128 v[168:171], v143 offset:2048
	ds_read_b128 v[174:177], v143 offset:3072
	v_lshl_add_u64 v[210:211], v[136:137], 0, s[28:29]
	s_add_i32 m0, s41, 0xc000
	ds_read_b128 v[178:181], v141
	ds_read_b128 v[182:185], v141 offset:1024
	ds_read_b128 v[186:189], v141 offset:2048
	ds_read_b128 v[190:193], v141 offset:3072
	ds_read_b128 v[194:197], v141 offset:4096
	ds_read_b128 v[198:201], v141 offset:5120
	ds_read_b128 v[202:205], v141 offset:6144
	ds_read_b128 v[206:209], v141 offset:7168
	global_load_lds_dwordx4 v[210:211], off
	v_lshl_add_u64 v[210:211], v[138:139], 0, s[28:29]
	s_add_i32 m0, s41, 0xe000
	s_nop 0
	global_load_lds_dwordx4 v[210:211], off
	s_waitcnt vmcnt(8)
	s_waitcnt lgkmcnt(0)
	s_setprio 1
	s_barrier
	s_waitcnt lgkmcnt(0)
	v_mfma_f32_16x16x32_bf16 v[126:129], v[144:147], v[178:181], v[126:129]
	v_mfma_f32_16x16x32_bf16 v[86:89], v[152:155], v[178:181], v[86:89]
	v_mfma_f32_16x16x32_bf16 v[114:117], v[144:147], v[186:189], v[114:117]
	v_mfma_f32_16x16x32_bf16 v[82:85], v[152:155], v[186:189], v[82:85]
	v_mfma_f32_16x16x32_bf16 v[122:125], v[144:147], v[194:197], v[122:125]
	v_mfma_f32_16x16x32_bf16 v[106:109], v[152:155], v[194:197], v[106:109]
	v_mfma_f32_16x16x32_bf16 v[118:121], v[144:147], v[202:205], v[118:121]
	v_mfma_f32_16x16x32_bf16 v[110:113], v[152:155], v[202:205], v[110:113]
	v_mfma_f32_16x16x32_bf16 v[126:129], v[148:151], v[182:185], v[126:129]
	v_mfma_f32_16x16x32_bf16 v[86:89], v[156:159], v[182:185], v[86:89]
	v_mfma_f32_16x16x32_bf16 v[114:117], v[148:151], v[190:193], v[114:117]
	v_mfma_f32_16x16x32_bf16 v[82:85], v[156:159], v[190:193], v[82:85]
	v_mfma_f32_16x16x32_bf16 v[122:125], v[148:151], v[198:201], v[122:125]
	v_mfma_f32_16x16x32_bf16 v[106:109], v[156:159], v[198:201], v[106:109]
	v_mfma_f32_16x16x32_bf16 v[118:121], v[148:151], v[206:209], v[118:121]
	v_mfma_f32_16x16x32_bf16 v[110:113], v[156:159], v[206:209], v[110:113]
	v_mfma_f32_16x16x32_bf16 v[22:25], v[160:163], v[178:181], v[22:25]
	v_mfma_f32_16x16x32_bf16 v[6:9], v[168:171], v[178:181], v[6:9]
	v_mfma_f32_16x16x32_bf16 v[18:21], v[160:163], v[186:189], v[18:21]
	v_mfma_f32_16x16x32_bf16 v[2:5], v[168:171], v[186:189], v[2:5]
	v_mfma_f32_16x16x32_bf16 v[38:41], v[160:163], v[194:197], v[38:41]
	v_mfma_f32_16x16x32_bf16 v[10:13], v[168:171], v[194:197], v[10:13]
	v_mfma_f32_16x16x32_bf16 v[34:37], v[160:163], v[202:205], v[34:37]
	v_mfma_f32_16x16x32_bf16 v[14:17], v[168:171], v[202:205], v[14:17]
	v_mfma_f32_16x16x32_bf16 v[22:25], v[164:167], v[182:185], v[22:25]
	v_mfma_f32_16x16x32_bf16 v[6:9], v[174:177], v[182:185], v[6:9]
	v_mfma_f32_16x16x32_bf16 v[18:21], v[164:167], v[190:193], v[18:21]
	v_mfma_f32_16x16x32_bf16 v[2:5], v[174:177], v[190:193], v[2:5]
	v_mfma_f32_16x16x32_bf16 v[38:41], v[164:167], v[198:201], v[38:41]
	v_mfma_f32_16x16x32_bf16 v[10:13], v[174:177], v[198:201], v[10:13]
	v_mfma_f32_16x16x32_bf16 v[34:37], v[164:167], v[206:209], v[34:37]
	v_mfma_f32_16x16x32_bf16 v[14:17], v[174:177], v[206:209], v[14:17]
	s_barrier
	s_setprio 0
	s_add_i32 s62, s64, s40
	v_lshl_add_u64 v[210:211], s[30:31], 0, v[0:1]
	s_mov_b32 m0, s62
	ds_read_b128 v[178:181], v141 offset:16384
	ds_read_b128 v[182:185], v141 offset:17408
	ds_read_b128 v[186:189], v141 offset:18432
	ds_read_b128 v[190:193], v141 offset:19456
	ds_read_b128 v[194:197], v141 offset:20480
	ds_read_b128 v[198:201], v141 offset:21504
	ds_read_b128 v[202:205], v141 offset:22528
	ds_read_b128 v[206:209], v141 offset:23552
	global_load_lds_dwordx4 v[210:211], off
	s_add_i32 m0, s62, 0x2000
	s_add_u32 s62, s30, 0x40000
	v_lshl_add_u64 v[212:213], s[30:31], 0, v[130:131]
	s_addc_u32 s63, s31, 0
	s_add_i32 s64, s65, s40
	global_load_lds_dwordx4 v[212:213], off
	v_lshl_add_u64 v[214:215], s[62:63], 0, v[0:1]
	s_mov_b32 m0, s64
	v_lshl_add_u64 v[220:221], s[34:35], 0, v[130:131]
	global_load_lds_dwordx4 v[214:215], off
	v_lshl_add_u64 v[214:215], s[62:63], 0, v[130:131]
	s_add_i32 m0, s64, 0x2000
	s_nop 0
	global_load_lds_dwordx4 v[214:215], off
	v_lshl_add_u64 v[214:215], s[34:35], 0, v[0:1]
	s_mov_b32 m0, s41
	s_nop 0
	global_load_lds_dwordx4 v[214:215], off
	s_mov_b32 m0, s42
	s_nop 0
	global_load_lds_dwordx4 v[220:221], off
	s_waitcnt vmcnt(8)
	s_waitcnt lgkmcnt(0)
	s_setprio 1
	s_barrier
; #define PG8_STAGE(bufoff, gbase, voff) do { _Pragma("unroll") for (int _i = 0; _i < 2; ++_i) \
;         __builtin_amdgcn_global_load_lds((const unsigned*)((const char*)(gbase) + (voff)[_i]), (PG8_LAS unsigned*)(lds + (bufoff) + ldsw + _i * 8192), 16, 0, 0); } while (0)
; #define PG8_LDA(dst, b, h) do { _Pragma("unroll") for (int m = 0; m < 4; ++m) _Pragma("unroll") for (int k = 0; k < 2; ++k) dst[m][k] = *(const PG8_LAS bf16x8*)(lds + PG8_SA(b, h) + aoff + m * 2048 + k * 1024); } while (0)
; #define PG8_LDB(dst, b, h) do { _Pragma("unroll") for (int n = 0; n < 2; ++n) _Pragma("unroll") for (int k = 0; k < 2; ++k) dst[n][k] = *(const PG8_LAS bf16x8*)(lds + PG8_SB(b, h) + boff + n * 2048 + k * 1024); } while (0)
; #define PG8_MMA(ai, bj, At, Bt) do { __builtin_amdgcn_s_setprio(1); _Pragma("unroll") for (int m = 0; m < 4; ++m) _Pragma("unroll") for (int n = 0; n < 2; ++n) _Pragma("unroll") for (int k = 0; k < 2; ++k) \
;         acc[ai][bj][m][n] = __builtin_amdgcn_mfma_f32_16x16x32_bf16(Bt[n][k], At[m][k], acc[ai][bj][m][n], 0, 0, 0); __builtin_amdgcn_s_setprio(0); } while (0)
; #define PG8_WAIT_V(n) asm volatile("s_waitcnt vmcnt(" #n ")" ::: "memory")
; #define PG8_WAIT_L(n) asm volatile("s_waitcnt lgkmcnt(" #n ")" ::: "memory")
; #define PG8_BAR __builtin_amdgcn_s_barrier()
; #define PG8_SCHED __builtin_amdgcn_sched_barrier(0)
; template <class Epi, class Sched, bool ALIGN_EPI = false, bool SP2 = false>
; __device__ __forceinline__ void gemm_phase(PG8_LAS unsigned char* lds, const Gemm g, const Sched& S, const Epi& E) {
;     ...
;             PG8_WAIT_V(8); PG8_WAIT_L(0); PG8_BAR; if (full) { PG8_MMA(1, 0, At, B0); PG8_MMA(1, 1, At, B1); } PG8_BAR; PG8_SCHED;
;             PG8_LDB(B0, 1, 0); PG8_LDB(B1, 1, 1); PG8_SCHED; PG8_LDA(At, 1, 0); PG8_STAGE(PG8_SA(0, 1), a2 + hstep, voffA);
;             PG8_WAIT_V(8); PG8_WAIT_L(0); PG8_BAR; PG8_MMA(0, 0, At, B0); PG8_MMA(0, 1, At, B1); PG8_BAR; PG8_SCHED;
	s_waitcnt lgkmcnt(0)
	v_mfma_f32_16x16x32_bf16 v[102:105], v[144:147], v[178:181], v[102:105]
	v_mfma_f32_16x16x32_bf16 v[98:101], v[152:155], v[178:181], v[98:101]
	v_mfma_f32_16x16x32_bf16 v[94:97], v[144:147], v[186:189], v[94:97]
	v_mfma_f32_16x16x32_bf16 v[90:93], v[152:155], v[186:189], v[90:93]
	v_mfma_f32_16x16x32_bf16 v[78:81], v[144:147], v[194:197], v[78:81]
	v_mfma_f32_16x16x32_bf16 v[74:77], v[152:155], v[194:197], v[74:77]
	v_mfma_f32_16x16x32_bf16 v[70:73], v[144:147], v[202:205], v[70:73]
	v_mfma_f32_16x16x32_bf16 v[66:69], v[152:155], v[202:205], v[66:69]
	v_mfma_f32_16x16x32_bf16 v[102:105], v[148:151], v[182:185], v[102:105]
	v_mfma_f32_16x16x32_bf16 v[98:101], v[156:159], v[182:185], v[98:101]
	v_mfma_f32_16x16x32_bf16 v[94:97], v[148:151], v[190:193], v[94:97]
	v_mfma_f32_16x16x32_bf16 v[90:93], v[156:159], v[190:193], v[90:93]
	v_mfma_f32_16x16x32_bf16 v[78:81], v[148:151], v[198:201], v[78:81]
	v_mfma_f32_16x16x32_bf16 v[74:77], v[156:159], v[198:201], v[74:77]
	v_mfma_f32_16x16x32_bf16 v[70:73], v[148:151], v[206:209], v[70:73]
	v_mfma_f32_16x16x32_bf16 v[66:69], v[156:159], v[206:209], v[66:69]
	v_mfma_f32_16x16x32_bf16 v[50:53], v[160:163], v[178:181], v[50:53]
	v_mfma_f32_16x16x32_bf16 v[26:29], v[168:171], v[178:181], v[26:29]
	v_mfma_f32_16x16x32_bf16 v[46:49], v[160:163], v[186:189], v[46:49]
	v_mfma_f32_16x16x32_bf16 v[30:33], v[168:171], v[186:189], v[30:33]
	v_mfma_f32_16x16x32_bf16 v[62:65], v[160:163], v[194:197], v[62:65]
	v_mfma_f32_16x16x32_bf16 v[54:57], v[168:171], v[194:197], v[54:57]
	v_mfma_f32_16x16x32_bf16 v[58:61], v[160:163], v[202:205], v[58:61]
	v_mfma_f32_16x16x32_bf16 v[42:45], v[168:171], v[202:205], v[42:45]
	v_mfma_f32_16x16x32_bf16 v[50:53], v[164:167], v[182:185], v[50:53]
	v_mfma_f32_16x16x32_bf16 v[26:29], v[174:177], v[182:185], v[26:29]
	v_mfma_f32_16x16x32_bf16 v[46:49], v[164:167], v[190:193], v[46:49]
	v_mfma_f32_16x16x32_bf16 v[30:33], v[174:177], v[190:193], v[30:33]
	v_mfma_f32_16x16x32_bf16 v[62:65], v[164:167], v[198:201], v[62:65]
	v_mfma_f32_16x16x32_bf16 v[54:57], v[174:177], v[198:201], v[54:57]
	v_mfma_f32_16x16x32_bf16 v[58:61], v[164:167], v[206:209], v[58:61]
	v_mfma_f32_16x16x32_bf16 v[42:45], v[174:177], v[206:209], v[42:45]
	s_barrier
	s_setprio 0
	s_add_i32 s62, 0, 0x18000
	v_add_u32_e32 v143, s62, v140
	s_add_i32 s63, 0, 0x1c000
	ds_read_b128 v[144:147], v143
	ds_read_b128 v[148:151], v143 offset:1024
	ds_read_b128 v[152:155], v143 offset:2048
	ds_read_b128 v[156:159], v143 offset:3072
	v_add_u32_e32 v143, s63, v140
	ds_read_b128 v[160:163], v143
	ds_read_b128 v[164:167], v143 offset:1024
	ds_read_b128 v[168:171], v143 offset:2048
	ds_read_b128 v[174:177], v143 offset:3072
	s_add_u32 s34, s34, 0x40000
	s_addc_u32 s35, s35, 0
	s_mov_b32 m0, s43
	v_lshl_add_u64 v[222:223], s[34:35], 0, v[0:1]
	ds_read_b128 v[178:181], v141 offset:32768
	ds_read_b128 v[182:185], v141 offset:33792
	ds_read_b128 v[186:189], v141 offset:34816
	ds_read_b128 v[190:193], v141 offset:35840
	ds_read_b128 v[194:197], v141 offset:36864
	ds_read_b128 v[198:201], v141 offset:37888
	ds_read_b128 v[202:205], v141 offset:38912
	ds_read_b128 v[206:209], v141 offset:39936
	global_load_lds_dwordx4 v[222:223], off
	v_lshl_add_u64 v[222:223], s[34:35], 0, v[130:131]
	s_mov_b32 m0, s44
	s_nop 0
	global_load_lds_dwordx4 v[222:223], off
	s_waitcnt vmcnt(8)
	s_waitcnt lgkmcnt(0)
	s_setprio 1
	s_barrier
	s_waitcnt lgkmcnt(0)
	v_mfma_f32_16x16x32_bf16 v[126:129], v[144:147], v[178:181], v[126:129]
	v_mfma_f32_16x16x32_bf16 v[86:89], v[152:155], v[178:181], v[86:89]
	v_mfma_f32_16x16x32_bf16 v[114:117], v[144:147], v[186:189], v[114:117]
	v_mfma_f32_16x16x32_bf16 v[82:85], v[152:155], v[186:189], v[82:85]
	v_mfma_f32_16x16x32_bf16 v[122:125], v[144:147], v[194:197], v[122:125]
	v_mfma_f32_16x16x32_bf16 v[106:109], v[152:155], v[194:197], v[106:109]
	v_mfma_f32_16x16x32_bf16 v[118:121], v[144:147], v[202:205], v[118:121]
	v_mfma_f32_16x16x32_bf16 v[110:113], v[152:155], v[202:205], v[110:113]
	v_mfma_f32_16x16x32_bf16 v[126:129], v[148:151], v[182:185], v[126:129]
	v_mfma_f32_16x16x32_bf16 v[86:89], v[156:159], v[182:185], v[86:89]
	v_mfma_f32_16x16x32_bf16 v[114:117], v[148:151], v[190:193], v[114:117]
	v_mfma_f32_16x16x32_bf16 v[82:85], v[156:159], v[190:193], v[82:85]
	v_mfma_f32_16x16x32_bf16 v[122:125], v[148:151], v[198:201], v[122:125]
	v_mfma_f32_16x16x32_bf16 v[106:109], v[156:159], v[198:201], v[106:109]
	v_mfma_f32_16x16x32_bf16 v[118:121], v[148:151], v[206:209], v[118:121]
	v_mfma_f32_16x16x32_bf16 v[110:113], v[156:159], v[206:209], v[110:113]
	v_mfma_f32_16x16x32_bf16 v[22:25], v[160:163], v[178:181], v[22:25]
	v_mfma_f32_16x16x32_bf16 v[6:9], v[168:171], v[178:181], v[6:9]
	v_mfma_f32_16x16x32_bf16 v[18:21], v[160:163], v[186:189], v[18:21]
	v_mfma_f32_16x16x32_bf16 v[2:5], v[168:171], v[186:189], v[2:5]
	v_mfma_f32_16x16x32_bf16 v[38:41], v[160:163], v[194:197], v[38:41]
	v_mfma_f32_16x16x32_bf16 v[10:13], v[168:171], v[194:197], v[10:13]
	v_mfma_f32_16x16x32_bf16 v[34:37], v[160:163], v[202:205], v[34:37]
	v_mfma_f32_16x16x32_bf16 v[14:17], v[168:171], v[202:205], v[14:17]
	v_mfma_f32_16x16x32_bf16 v[22:25], v[164:167], v[182:185], v[22:25]
	v_mfma_f32_16x16x32_bf16 v[6:9], v[174:177], v[182:185], v[6:9]
	v_mfma_f32_16x16x32_bf16 v[18:21], v[164:167], v[190:193], v[18:21]
	v_mfma_f32_16x16x32_bf16 v[2:5], v[174:177], v[190:193], v[2:5]
	v_mfma_f32_16x16x32_bf16 v[38:41], v[164:167], v[198:201], v[38:41]
	v_mfma_f32_16x16x32_bf16 v[10:13], v[174:177], v[198:201], v[10:13]
	v_mfma_f32_16x16x32_bf16 v[34:37], v[164:167], v[206:209], v[34:37]
	v_mfma_f32_16x16x32_bf16 v[14:17], v[174:177], v[206:209], v[14:17]
	s_barrier
; #define PG8_STAGE(bufoff, gbase, voff) do { _Pragma("unroll") for (int _i = 0; _i < 2; ++_i) \
;         __builtin_amdgcn_global_load_lds((const unsigned*)((const char*)(gbase) + (voff)[_i]), (PG8_LAS unsigned*)(lds + (bufoff) + ldsw + _i * 8192), 16, 0, 0); } while (0)
; #define PG8_LDA(dst, b, h) do { _Pragma("unroll") for (int m = 0; m < 4; ++m) _Pragma("unroll") for (int k = 0; k < 2; ++k) dst[m][k] = *(const PG8_LAS bf16x8*)(lds + PG8_SA(b, h) + aoff + m * 2048 + k * 1024); } while (0)
; #define PG8_MMA(ai, bj, At, Bt) do { __builtin_amdgcn_s_setprio(1); _Pragma("unroll") for (int m = 0; m < 4; ++m) _Pragma("unroll") for (int n = 0; n < 2; ++n) _Pragma("unroll") for (int k = 0; k < 2; ++k) \
;         acc[ai][bj][m][n] = __builtin_amdgcn_mfma_f32_16x16x32_bf16(Bt[n][k], At[m][k], acc[ai][bj][m][n], 0, 0, 0); __builtin_amdgcn_s_setprio(0); } while (0)
; #define PG8_WAIT_V(n) asm volatile("s_waitcnt vmcnt(" #n ")" ::: "memory")
; #define PG8_WAIT_L(n) asm volatile("s_waitcnt lgkmcnt(" #n ")" ::: "memory")
; #define PG8_BAR __builtin_amdgcn_s_barrier()
; #define PG8_SCHED __builtin_amdgcn_sched_barrier(0)
; template <class Epi, class Sched, bool ALIGN_EPI = false, bool SP2 = false>
; __device__ __forceinline__ void gemm_phase(PG8_LAS unsigned char* lds, const Gemm g, const Sched& S, const Epi& E) {
;     ...
;             if (full) PG8_LDA(At, 1, 1); PG8_STAGE(PG8_SB(1, 0), b3, voffB); PG8_STAGE(PG8_SB(1, 1), b3 + hstep, voffB); PG8_STAGE(PG8_SA(1, 0), a3, voffA);
;             PG8_WAIT_V(8); PG8_WAIT_L(0); PG8_BAR; if (full) { PG8_MMA(1, 0, At, B0); PG8_MMA(1, 1, At, B1); } PG8_BAR; PG8_SCHED;
;     ...
;         if (!Sched::KEEP || (nxt.pn >> 2) == 0) {
; #pragma unroll
;         for (int a = 0; a < 2; ++a)
; #pragma unroll
;             for (int b = 0; b < 2; ++b)
; #pragma unroll
;                 for (int m = 0; m < 4; ++m)
; #pragma unroll
;                     for (int n = 0; n < 2; ++n) acc[a][b][m][n] = (f32x4){0.f, 0.f, 0.f, 0.f};
;         }
	s_setprio 0
	s_add_i32 s34, s62, s40
	v_lshl_add_u64 v[210:211], v[210:211], 0, s[52:53]
	s_mov_b32 m0, s34
	ds_read_b128 v[178:181], v141 offset:49152
	ds_read_b128 v[182:185], v141 offset:50176
	ds_read_b128 v[186:189], v141 offset:51200
	ds_read_b128 v[190:193], v141 offset:52224
	ds_read_b128 v[194:197], v141 offset:53248
	ds_read_b128 v[198:201], v141 offset:54272
	ds_read_b128 v[202:205], v141 offset:55296
	ds_read_b128 v[206:209], v141 offset:56320
	global_load_lds_dwordx4 v[210:211], off
	s_add_i32 m0, s34, 0x2000
	s_add_u32 s30, s30, 0x40080
	v_lshl_add_u64 v[210:211], v[212:213], 0, s[52:53]
	s_addc_u32 s31, s31, 0
	s_add_i32 s34, s63, s40
	global_load_lds_dwordx4 v[210:211], off
	v_lshl_add_u64 v[210:211], s[30:31], 0, v[0:1]
	s_mov_b32 m0, s34
	s_nop 0
	global_load_lds_dwordx4 v[210:211], off
	v_lshl_add_u64 v[210:211], s[30:31], 0, v[130:131]
	s_add_i32 m0, s34, 0x2000
	s_nop 0
	global_load_lds_dwordx4 v[210:211], off
	v_lshl_add_u64 v[210:211], v[214:215], 0, s[52:53]
	s_mov_b32 m0, s48
	s_nop 0
	global_load_lds_dwordx4 v[210:211], off
	v_lshl_add_u64 v[210:211], v[220:221], 0, s[52:53]
	s_mov_b32 m0, s49
	s_nop 0
	global_load_lds_dwordx4 v[210:211], off
	s_waitcnt vmcnt(8)
	s_waitcnt lgkmcnt(0)
	s_setprio 1
	s_barrier
	s_waitcnt lgkmcnt(0)
	v_mfma_f32_16x16x32_bf16 v[102:105], v[144:147], v[178:181], v[102:105]
	v_mfma_f32_16x16x32_bf16 v[98:101], v[152:155], v[178:181], v[98:101]
	v_mfma_f32_16x16x32_bf16 v[94:97], v[144:147], v[186:189], v[94:97]
	v_mfma_f32_16x16x32_bf16 v[90:93], v[152:155], v[186:189], v[90:93]
	v_mfma_f32_16x16x32_bf16 v[78:81], v[144:147], v[194:197], v[78:81]
	v_mfma_f32_16x16x32_bf16 v[74:77], v[152:155], v[194:197], v[74:77]
	v_mfma_f32_16x16x32_bf16 v[70:73], v[144:147], v[202:205], v[70:73]
	v_mfma_f32_16x16x32_bf16 v[66:69], v[152:155], v[202:205], v[66:69]
	v_mfma_f32_16x16x32_bf16 v[102:105], v[148:151], v[182:185], v[102:105]
	v_mfma_f32_16x16x32_bf16 v[98:101], v[156:159], v[182:185], v[98:101]
	v_mfma_f32_16x16x32_bf16 v[94:97], v[148:151], v[190:193], v[94:97]
	v_mfma_f32_16x16x32_bf16 v[90:93], v[156:159], v[190:193], v[90:93]
	v_mfma_f32_16x16x32_bf16 v[78:81], v[148:151], v[198:201], v[78:81]
	v_mfma_f32_16x16x32_bf16 v[74:77], v[156:159], v[198:201], v[74:77]
	v_mfma_f32_16x16x32_bf16 v[70:73], v[148:151], v[206:209], v[70:73]
	v_mfma_f32_16x16x32_bf16 v[66:69], v[156:159], v[206:209], v[66:69]
	v_mfma_f32_16x16x32_bf16 v[50:53], v[160:163], v[178:181], v[50:53]
	v_mfma_f32_16x16x32_bf16 v[26:29], v[168:171], v[178:181], v[26:29]
	v_mfma_f32_16x16x32_bf16 v[46:49], v[160:163], v[186:189], v[46:49]
	v_mfma_f32_16x16x32_bf16 v[30:33], v[168:171], v[186:189], v[30:33]
	v_mfma_f32_16x16x32_bf16 v[62:65], v[160:163], v[194:197], v[62:65]
	v_mfma_f32_16x16x32_bf16 v[54:57], v[168:171], v[194:197], v[54:57]
	v_mfma_f32_16x16x32_bf16 v[58:61], v[160:163], v[202:205], v[58:61]
	v_mfma_f32_16x16x32_bf16 v[42:45], v[168:171], v[202:205], v[42:45]
	v_mfma_f32_16x16x32_bf16 v[50:53], v[164:167], v[182:185], v[50:53]
	v_mfma_f32_16x16x32_bf16 v[26:29], v[174:177], v[182:185], v[26:29]
	v_mfma_f32_16x16x32_bf16 v[46:49], v[164:167], v[190:193], v[46:49]
	v_mfma_f32_16x16x32_bf16 v[30:33], v[174:177], v[190:193], v[30:33]
	v_mfma_f32_16x16x32_bf16 v[62:65], v[164:167], v[198:201], v[62:65]
	v_mfma_f32_16x16x32_bf16 v[54:57], v[174:177], v[198:201], v[54:57]
	v_mfma_f32_16x16x32_bf16 v[58:61], v[164:167], v[206:209], v[58:61]
	v_mfma_f32_16x16x32_bf16 v[42:45], v[174:177], v[206:209], v[42:45]
	s_barrier
	s_setprio 0
	s_add_i32 s61, s61, 2
	s_add_u32 s28, s28, 0x100
	s_addc_u32 s29, s29, 0
	s_cmp_gt_u32 s61, 13
	s_cbranch_scc0 .LBB0_1149
	s_add_u32 s28, s57, 0xffffff00
	s_addc_u32 s29, s58, -1
	s_andn2_b64 vcc, exec, s[6:7]
	s_cbranch_vccnz .LBB0_1152
	v_mov_b32_e32 v42, 0
	s_mov_b32 s14, s20
	s_mov_b32 s12, s22
	s_mov_b64 s[18:19], s[26:27]
	s_mov_b32 s55, s56
	v_mov_b32_e32 v43, v42
	v_mov_b32_e32 v44, v42
	v_mov_b32_e32 v45, v42
	v_mov_b32_e32 v58, v42
	v_mov_b32_e32 v59, v42
	v_mov_b32_e32 v60, v42
	v_mov_b32_e32 v61, v42
	v_mov_b32_e32 v54, v42
	v_mov_b32_e32 v55, v42
	v_mov_b32_e32 v56, v42
	v_mov_b32_e32 v57, v42
	v_mov_b32_e32 v62, v42
	v_mov_b32_e32 v63, v42
	v_mov_b32_e32 v64, v42
	v_mov_b32_e32 v65, v42
	v_mov_b32_e32 v30, v42
	v_mov_b32_e32 v31, v42
	v_mov_b32_e32 v32, v42
	v_mov_b32_e32 v33, v42
	v_mov_b32_e32 v46, v42
	v_mov_b32_e32 v47, v42
	v_mov_b32_e32 v48, v42
	v_mov_b32_e32 v49, v42
	v_mov_b32_e32 v26, v42
	v_mov_b32_e32 v27, v42
	v_mov_b32_e32 v28, v42
	v_mov_b32_e32 v29, v42
	v_mov_b32_e32 v50, v42
	v_mov_b32_e32 v51, v42
	v_mov_b32_e32 v52, v42
	v_mov_b32_e32 v53, v42
	v_mov_b32_e32 v66, v42
	v_mov_b32_e32 v67, v42
	v_mov_b32_e32 v68, v42
	v_mov_b32_e32 v69, v42
	v_mov_b32_e32 v70, v42
	v_mov_b32_e32 v71, v42
	v_mov_b32_e32 v72, v42
	v_mov_b32_e32 v73, v42
	v_mov_b32_e32 v74, v42
	v_mov_b32_e32 v75, v42
	v_mov_b32_e32 v76, v42
	v_mov_b32_e32 v77, v42
	v_mov_b32_e32 v78, v42
	v_mov_b32_e32 v79, v42
	v_mov_b32_e32 v80, v42
	v_mov_b32_e32 v81, v42
	v_mov_b32_e32 v90, v42
	v_mov_b32_e32 v91, v42
	v_mov_b32_e32 v92, v42
	v_mov_b32_e32 v93, v42
	v_mov_b32_e32 v94, v42
	v_mov_b32_e32 v95, v42
	v_mov_b32_e32 v96, v42
	v_mov_b32_e32 v97, v42
	v_mov_b32_e32 v98, v42
	v_mov_b32_e32 v99, v42
	v_mov_b32_e32 v100, v42
	v_mov_b32_e32 v101, v42
	v_mov_b32_e32 v102, v42
	v_mov_b32_e32 v103, v42
	v_mov_b32_e32 v104, v42
	v_mov_b32_e32 v105, v42
	v_mov_b32_e32 v14, v42
	v_mov_b32_e32 v15, v42
	v_mov_b32_e32 v16, v42
	v_mov_b32_e32 v17, v42
	v_mov_b32_e32 v34, v42
	v_mov_b32_e32 v35, v42
	v_mov_b32_e32 v36, v42
	v_mov_b32_e32 v37, v42
	v_mov_b32_e32 v10, v42
	v_mov_b32_e32 v11, v42
	v_mov_b32_e32 v12, v42
	v_mov_b32_e32 v13, v42
	v_mov_b32_e32 v38, v42
	v_mov_b32_e32 v39, v42
	v_mov_b32_e32 v40, v42
	v_mov_b32_e32 v41, v42
	v_mov_b32_e32 v2, v42
	v_mov_b32_e32 v3, v42
	v_mov_b32_e32 v4, v42
	v_mov_b32_e32 v5, v42
	v_mov_b32_e32 v18, v42
	v_mov_b32_e32 v19, v42
	v_mov_b32_e32 v20, v42
	v_mov_b32_e32 v21, v42
	v_mov_b32_e32 v6, v42
	v_mov_b32_e32 v7, v42
	v_mov_b32_e32 v8, v42
	v_mov_b32_e32 v9, v42
	v_mov_b32_e32 v22, v42
	v_mov_b32_e32 v23, v42
	v_mov_b32_e32 v24, v42
	v_mov_b32_e32 v25, v42
	v_mov_b32_e32 v110, v42
	v_mov_b32_e32 v111, v42
	v_mov_b32_e32 v112, v42
	v_mov_b32_e32 v113, v42
	v_mov_b32_e32 v118, v42
	v_mov_b32_e32 v119, v42
	v_mov_b32_e32 v120, v42
	v_mov_b32_e32 v121, v42
	v_mov_b32_e32 v106, v42
	v_mov_b32_e32 v107, v42
	v_mov_b32_e32 v108, v42
	v_mov_b32_e32 v109, v42
	v_mov_b32_e32 v122, v42
	v_mov_b32_e32 v123, v42
	v_mov_b32_e32 v124, v42
	v_mov_b32_e32 v125, v42
	v_mov_b32_e32 v82, v42
	v_mov_b32_e32 v83, v42
	v_mov_b32_e32 v84, v42
	v_mov_b32_e32 v85, v42
	v_mov_b32_e32 v114, v42
	v_mov_b32_e32 v115, v42
	v_mov_b32_e32 v116, v42
	v_mov_b32_e32 v117, v42
	v_mov_b32_e32 v86, v42
	v_mov_b32_e32 v87, v42
	v_mov_b32_e32 v88, v42
	v_mov_b32_e32 v89, v42
	v_mov_b32_e32 v126, v42
	v_mov_b32_e32 v127, v42
	v_mov_b32_e32 v128, v42
	v_mov_b32_e32 v129, v42
	s_branch .LBB0_1153
